# GEMM K-loops: per-K-step global prefetch block (16 loads + address math) moved off the barrier edge into the slice-0 MFMA shadow
# speedup vs baseline: 1.1142x; 1.0154x over previous
; #define GLOAD(RA, RB, kt) { _Pragma("unroll") for (int i = 0; i < 8; ++i) { const int ia = (tail && i >= 4) ? i - 4 : i; \
;     RA[i] = *(const u32x4*)(abase + ((size_t)(32 * ia) * lda + (kt) * 64) * 2 + aoff); RB[i] = *(const u32x4*)(bbase + ((size_t)(32 * i) * K + (kt) * 64) * 2 + boff); } }
; #define LWRITE(RA, RB, buf) { char* as_ = lds + (buf) * 2 * G_TILE; char* bs_ = as_ + G_TILE; _Pragma("unroll") for (int i = 0; i < 8; ++i) { *(u32x4*)(as_ + (lrow + 32 * i) * GS_B + lch * 16) = RA[i]; *(u32x4*)(bs_ + (lrow + 32 * i) * GS_B + lch * 16) = RB[i]; } }
; template <int EPI>
; DEV void gemm_tile(CParams& p, int layer, const bf16_t* __restrict__ A, int lda, const bf16_t* __restrict__ Bt, int K, int m0, int n0, int nt, char* lds, const int swave) {
;     ...
;   GLOAD(ra0, rb0, 0); GLOAD(ra1, rb1, 1); LWRITE(ra0, rb0, 0); __syncthreads();
; #pragma unroll 1
;   for (int kt = 0; kt < nk; kt += 2) {
;     if (kt + 2 < nk) GLOAD(ra0, rb0, kt + 2);
;     COMPUTE(0, ra1, rb1, 1, true);
.LBB0_101:
	s_cmp_eq_u32 s36, 0
	s_cbranch_scc0 .Lzi_i1
	ds_read_b128 v[188:191], v49
	ds_read_b128 v[192:195], v49 offset:4608
	ds_read_b128 v[196:199], v49 offset:9216
	ds_read_b128 v[200:203], v49 offset:13824
	ds_read_b128 v[184:187], v48
	ds_read_b128 v[204:207], v48 offset:4608
	s_waitcnt lgkmcnt(1)
	v_mfma_f32_32x32x16_bf16 a[192:207], v[184:187], v[188:191], 0
	v_mfma_f32_32x32x16_bf16 a[128:143], v[184:187], v[192:195], 0
	v_mfma_f32_32x32x16_bf16 a[64:79], v[184:187], v[196:199], 0
	v_mfma_f32_32x32x16_bf16 a[0:15], v[184:187], v[200:203], 0
	ds_read_b128 v[184:187], v48 offset:9216
	ds_read_b128 v[208:211], v49 offset:32
	ds_read_b128 v[212:215], v49 offset:4640
	v_lshl_add_u64 v[50:51], v[0:1], 0, s[34:35]
	global_load_dwordx4 v[52:55], v[50:51], off
	v_lshl_add_u64 v[50:51], v[2:3], 0, s[34:35]
	s_or_b32 s2, s34, 0x10000
	s_mov_b32 s3, s35
	global_load_dwordx4 v[56:59], v[50:51], off
	v_lshl_add_u64 v[50:51], v[0:1], 0, s[2:3]
	global_load_dwordx4 v[60:63], v[50:51], off
	v_lshl_add_u64 v[50:51], v[2:3], 0, s[2:3]
	s_or_b32 s2, s34, 0x20000
	global_load_dwordx4 v[68:71], v[50:51], off
	s_waitcnt lgkmcnt(3)
	v_mfma_f32_32x32x16_bf16 a[208:223], v[204:207], v[188:191], 0
	v_mfma_f32_32x32x16_bf16 a[144:159], v[204:207], v[192:195], 0
	v_mfma_f32_32x32x16_bf16 a[80:95], v[204:207], v[196:199], 0
	v_mfma_f32_32x32x16_bf16 a[16:31], v[204:207], v[200:203], 0
	ds_read_b128 v[204:207], v48 offset:13824
	ds_read_b128 v[216:219], v49 offset:9248
	ds_read_b128 v[220:223], v49 offset:13856
	v_lshl_add_u64 v[50:51], v[0:1], 0, s[2:3]
	global_load_dwordx4 v[72:75], v[50:51], off
	v_lshl_add_u64 v[50:51], v[2:3], 0, s[2:3]
	s_or_b32 s2, s34, 0x30000
	global_load_dwordx4 v[76:79], v[50:51], off
	v_lshl_add_u64 v[50:51], v[0:1], 0, s[2:3]
	global_load_dwordx4 v[80:83], v[50:51], off
	v_lshl_add_u64 v[50:51], v[2:3], 0, s[2:3]
	s_or_b32 s2, s34, 0x40000
	global_load_dwordx4 v[84:87], v[50:51], off
	s_waitcnt lgkmcnt(5)
	v_mfma_f32_32x32x16_bf16 a[224:239], v[184:187], v[188:191], 0
	v_mfma_f32_32x32x16_bf16 a[160:175], v[184:187], v[192:195], 0
	v_mfma_f32_32x32x16_bf16 a[96:111], v[184:187], v[196:199], 0
	v_mfma_f32_32x32x16_bf16 a[32:47], v[184:187], v[200:203], 0
	ds_read_b128 v[184:187], v48 offset:32
	v_lshl_add_u64 v[50:51], v[0:1], 0, s[2:3]
	global_load_dwordx4 v[88:91], v[50:51], off
	v_lshl_add_u64 v[50:51], v[2:3], 0, s[2:3]
	s_or_b32 s2, s34, 0x50000
	global_load_dwordx4 v[92:95], v[50:51], off
	v_lshl_add_u64 v[50:51], v[0:1], 0, s[2:3]
	global_load_dwordx4 v[96:99], v[50:51], off
	v_lshl_add_u64 v[50:51], v[2:3], 0, s[2:3]
	s_or_b32 s2, s34, 0x60000
	global_load_dwordx4 v[108:111], v[50:51], off
	s_waitcnt lgkmcnt(3)
	v_mfma_f32_32x32x16_bf16 a[240:255], v[204:207], v[188:191], 0
	v_mfma_f32_32x32x16_bf16 a[176:191], v[204:207], v[192:195], 0
	v_mfma_f32_32x32x16_bf16 a[112:127], v[204:207], v[196:199], 0
	v_mfma_f32_32x32x16_bf16 a[48:63], v[204:207], v[200:203], 0
	ds_read_b128 v[204:207], v48 offset:4640
	v_lshl_add_u64 v[50:51], v[0:1], 0, s[2:3]
	global_load_dwordx4 v[124:127], v[50:51], off
	v_lshl_add_u64 v[50:51], v[2:3], 0, s[2:3]
	s_or_b32 s34, s34, 0x70000
	global_load_dwordx4 v[144:147], v[50:51], off
	v_lshl_add_u64 v[50:51], v[0:1], 0, s[34:35]
	global_load_dwordx4 v[160:163], v[50:51], off
	v_lshl_add_u64 v[50:51], v[2:3], 0, s[34:35]
	global_load_dwordx4 v[180:183], v[50:51], off
	s_waitcnt vmcnt(31)
	ds_write_b128 v31, v[100:103]
	s_waitcnt vmcnt(30)
	ds_write_b128 v32, v[104:107]
	s_waitcnt vmcnt(29)
	ds_write_b128 v41, v[112:115]
	s_waitcnt vmcnt(28)
	ds_write_b128 v42, v[116:119]
	s_waitcnt lgkmcnt(5)
	v_mfma_f32_32x32x16_bf16 a[192:207], v[184:187], v[208:211], a[192:207]
	v_mfma_f32_32x32x16_bf16 a[128:143], v[184:187], v[212:215], a[128:143]
	v_mfma_f32_32x32x16_bf16 a[64:79], v[184:187], v[216:219], a[64:79]
	v_mfma_f32_32x32x16_bf16 a[0:15], v[184:187], v[220:223], a[0:15]
	ds_read_b128 v[184:187], v48 offset:9248
	ds_read_b128 v[188:191], v49 offset:64
	ds_read_b128 v[192:195], v49 offset:4672
	s_waitcnt lgkmcnt(7)
	v_mfma_f32_32x32x16_bf16 a[208:223], v[204:207], v[208:211], a[208:223]
	v_mfma_f32_32x32x16_bf16 a[144:159], v[204:207], v[212:215], a[144:159]
	v_mfma_f32_32x32x16_bf16 a[80:95], v[204:207], v[216:219], a[80:95]
	v_mfma_f32_32x32x16_bf16 a[16:31], v[204:207], v[220:223], a[16:31]
	ds_read_b128 v[204:207], v48 offset:13856
	ds_read_b128 v[196:199], v49 offset:9280
	ds_read_b128 v[200:203], v49 offset:13888
	s_waitcnt lgkmcnt(5)
	v_mfma_f32_32x32x16_bf16 a[224:239], v[184:187], v[208:211], a[224:239]
	v_mfma_f32_32x32x16_bf16 a[160:175], v[184:187], v[212:215], a[160:175]
	v_mfma_f32_32x32x16_bf16 a[96:111], v[184:187], v[216:219], a[96:111]
	v_mfma_f32_32x32x16_bf16 a[32:47], v[184:187], v[220:223], a[32:47]
	ds_read_b128 v[184:187], v48 offset:64
	s_waitcnt lgkmcnt(3)
	v_mfma_f32_32x32x16_bf16 a[240:255], v[204:207], v[208:211], a[240:255]
	v_mfma_f32_32x32x16_bf16 a[176:191], v[204:207], v[212:215], a[176:191]
	v_mfma_f32_32x32x16_bf16 a[112:127], v[204:207], v[216:219], a[112:127]
	v_mfma_f32_32x32x16_bf16 a[48:63], v[204:207], v[220:223], a[48:63]
	ds_read_b128 v[204:207], v48 offset:4672
	s_waitcnt vmcnt(27)
	ds_write_b128 v37, v[120:123]
	s_waitcnt vmcnt(26)
	ds_write_b128 v38, v[128:131]
	s_waitcnt vmcnt(25)
	ds_write_b128 v39, v[132:135]
	s_waitcnt vmcnt(24)
	ds_write_b128 v40, v[136:139]
	s_waitcnt lgkmcnt(5)
	v_mfma_f32_32x32x16_bf16 a[192:207], v[184:187], v[188:191], a[192:207]
	v_mfma_f32_32x32x16_bf16 a[128:143], v[184:187], v[192:195], a[128:143]
	v_mfma_f32_32x32x16_bf16 a[64:79], v[184:187], v[196:199], a[64:79]
	v_mfma_f32_32x32x16_bf16 a[0:15], v[184:187], v[200:203], a[0:15]
	ds_read_b128 v[184:187], v48 offset:9280
	ds_read_b128 v[208:211], v49 offset:96
	ds_read_b128 v[212:215], v49 offset:4704
	s_waitcnt lgkmcnt(7)
; #define GLOAD(RA, RB, kt) { _Pragma("unroll") for (int i = 0; i < 8; ++i) { const int ia = (tail && i >= 4) ? i - 4 : i; \
;     RA[i] = *(const u32x4*)(abase + ((size_t)(32 * ia) * lda + (kt) * 64) * 2 + aoff); RB[i] = *(const u32x4*)(bbase + ((size_t)(32 * i) * K + (kt) * 64) * 2 + boff); } }
; #define LWRITE(RA, RB, buf) { char* as_ = lds + (buf) * 2 * G_TILE; char* bs_ = as_ + G_TILE; _Pragma("unroll") for (int i = 0; i < 8; ++i) { *(u32x4*)(as_ + (lrow + 32 * i) * GS_B + lch * 16) = RA[i]; *(u32x4*)(bs_ + (lrow + 32 * i) * GS_B + lch * 16) = RB[i]; } }
; template <int EPI>
; DEV void gemm_tile(CParams& p, int layer, const bf16_t* __restrict__ A, int lda, const bf16_t* __restrict__ Bt, int K, int m0, int n0, int nt, char* lds, const int swave) {
;     ...
;   GLOAD(ra0, rb0, 0); GLOAD(ra1, rb1, 1); LWRITE(ra0, rb0, 0); __syncthreads();
; #pragma unroll 1
;   for (int kt = 0; kt < nk; kt += 2) {
;     if (kt + 2 < nk) GLOAD(ra0, rb0, kt + 2);
;     COMPUTE(0, ra1, rb1, 1, true);
	v_mfma_f32_32x32x16_bf16 a[208:223], v[204:207], v[188:191], a[208:223]
	v_mfma_f32_32x32x16_bf16 a[144:159], v[204:207], v[192:195], a[144:159]
	v_mfma_f32_32x32x16_bf16 a[80:95], v[204:207], v[196:199], a[80:95]
	v_mfma_f32_32x32x16_bf16 a[16:31], v[204:207], v[200:203], a[16:31]
	ds_read_b128 v[204:207], v48 offset:13888
	ds_read_b128 v[216:219], v49 offset:9312
	ds_read_b128 v[220:223], v49 offset:13920
	s_waitcnt lgkmcnt(5)
	v_mfma_f32_32x32x16_bf16 a[224:239], v[184:187], v[188:191], a[224:239]
	v_mfma_f32_32x32x16_bf16 a[160:175], v[184:187], v[192:195], a[160:175]
	v_mfma_f32_32x32x16_bf16 a[96:111], v[184:187], v[196:199], a[96:111]
	v_mfma_f32_32x32x16_bf16 a[32:47], v[184:187], v[200:203], a[32:47]
	ds_read_b128 v[184:187], v48 offset:96
	s_waitcnt lgkmcnt(3)
	v_mfma_f32_32x32x16_bf16 a[240:255], v[204:207], v[188:191], a[240:255]
	v_mfma_f32_32x32x16_bf16 a[176:191], v[204:207], v[192:195], a[176:191]
	v_mfma_f32_32x32x16_bf16 a[112:127], v[204:207], v[196:199], a[112:127]
	v_mfma_f32_32x32x16_bf16 a[48:63], v[204:207], v[200:203], a[48:63]
	ds_read_b128 v[204:207], v48 offset:4704
	s_waitcnt vmcnt(23)
	ds_write_b128 v33, v[140:143]
	s_waitcnt vmcnt(22)
	ds_write_b128 v34, v[148:151]
	s_waitcnt vmcnt(21)
	ds_write_b128 v35, v[152:155]
	s_waitcnt vmcnt(20)
	ds_write_b128 v36, v[156:159]
	s_waitcnt lgkmcnt(5)
	v_mfma_f32_32x32x16_bf16 a[192:207], v[184:187], v[208:211], a[192:207]
	v_mfma_f32_32x32x16_bf16 a[128:143], v[184:187], v[212:215], a[128:143]
	v_mfma_f32_32x32x16_bf16 a[64:79], v[184:187], v[216:219], a[64:79]
	v_mfma_f32_32x32x16_bf16 a[0:15], v[184:187], v[220:223], a[0:15]
	ds_read_b128 v[184:187], v48 offset:9312
	s_waitcnt lgkmcnt(5)
	v_mfma_f32_32x32x16_bf16 a[208:223], v[204:207], v[208:211], a[208:223]
	v_mfma_f32_32x32x16_bf16 a[144:159], v[204:207], v[212:215], a[144:159]
	v_mfma_f32_32x32x16_bf16 a[80:95], v[204:207], v[216:219], a[80:95]
	v_mfma_f32_32x32x16_bf16 a[16:31], v[204:207], v[220:223], a[16:31]
	ds_read_b128 v[204:207], v48 offset:13920
	s_waitcnt lgkmcnt(1)
	v_mfma_f32_32x32x16_bf16 a[224:239], v[184:187], v[208:211], a[224:239]
	v_mfma_f32_32x32x16_bf16 a[160:175], v[184:187], v[212:215], a[160:175]
	v_mfma_f32_32x32x16_bf16 a[96:111], v[184:187], v[216:219], a[96:111]
	v_mfma_f32_32x32x16_bf16 a[32:47], v[184:187], v[220:223], a[32:47]
	s_waitcnt lgkmcnt(0)
	v_mfma_f32_32x32x16_bf16 a[240:255], v[204:207], v[208:211], a[240:255]
	v_mfma_f32_32x32x16_bf16 a[176:191], v[204:207], v[212:215], a[176:191]
	v_mfma_f32_32x32x16_bf16 a[112:127], v[204:207], v[216:219], a[112:127]
	v_mfma_f32_32x32x16_bf16 a[48:63], v[204:207], v[220:223], a[48:63]
	s_waitcnt vmcnt(19)
	ds_write_b128 v43, v[164:167]
	s_waitcnt vmcnt(18)
	ds_write_b128 v44, v[168:171]
	s_waitcnt vmcnt(17)
	ds_write_b128 v45, v[172:175]
	s_waitcnt vmcnt(16)
	ds_write_b128 v46, v[176:179]
	s_branch .LBB0_117
.Lzi_i1:
	ds_read_b128 v[188:191], v49
	ds_read_b128 v[192:195], v49 offset:4608
	ds_read_b128 v[196:199], v49 offset:9216
	ds_read_b128 v[200:203], v49 offset:13824
	ds_read_b128 v[184:187], v48
	ds_read_b128 v[204:207], v48 offset:4608
	s_waitcnt lgkmcnt(1)
	v_mfma_f32_32x32x16_bf16 a[192:207], v[184:187], v[188:191], a[192:207]
	v_mfma_f32_32x32x16_bf16 a[128:143], v[184:187], v[192:195], a[128:143]
	v_mfma_f32_32x32x16_bf16 a[64:79], v[184:187], v[196:199], a[64:79]
	v_mfma_f32_32x32x16_bf16 a[0:15], v[184:187], v[200:203], a[0:15]
	ds_read_b128 v[184:187], v48 offset:9216
	ds_read_b128 v[208:211], v49 offset:32
	ds_read_b128 v[212:215], v49 offset:4640
	v_lshl_add_u64 v[50:51], v[0:1], 0, s[34:35]
	global_load_dwordx4 v[52:55], v[50:51], off
	v_lshl_add_u64 v[50:51], v[2:3], 0, s[34:35]
	s_or_b32 s2, s34, 0x10000
	s_mov_b32 s3, s35
	global_load_dwordx4 v[56:59], v[50:51], off
	v_lshl_add_u64 v[50:51], v[0:1], 0, s[2:3]
	global_load_dwordx4 v[60:63], v[50:51], off
	v_lshl_add_u64 v[50:51], v[2:3], 0, s[2:3]
	s_or_b32 s2, s34, 0x20000
	global_load_dwordx4 v[68:71], v[50:51], off
	s_waitcnt lgkmcnt(3)
	v_mfma_f32_32x32x16_bf16 a[208:223], v[204:207], v[188:191], a[208:223]
	v_mfma_f32_32x32x16_bf16 a[144:159], v[204:207], v[192:195], a[144:159]
	v_mfma_f32_32x32x16_bf16 a[80:95], v[204:207], v[196:199], a[80:95]
	v_mfma_f32_32x32x16_bf16 a[16:31], v[204:207], v[200:203], a[16:31]
	ds_read_b128 v[204:207], v48 offset:13824
	ds_read_b128 v[216:219], v49 offset:9248
	ds_read_b128 v[220:223], v49 offset:13856
	v_lshl_add_u64 v[50:51], v[0:1], 0, s[2:3]
	global_load_dwordx4 v[72:75], v[50:51], off
	v_lshl_add_u64 v[50:51], v[2:3], 0, s[2:3]
	s_or_b32 s2, s34, 0x30000
	global_load_dwordx4 v[76:79], v[50:51], off
	v_lshl_add_u64 v[50:51], v[0:1], 0, s[2:3]
	global_load_dwordx4 v[80:83], v[50:51], off
	v_lshl_add_u64 v[50:51], v[2:3], 0, s[2:3]
	s_or_b32 s2, s34, 0x40000
	global_load_dwordx4 v[84:87], v[50:51], off
	s_waitcnt lgkmcnt(5)
	v_mfma_f32_32x32x16_bf16 a[224:239], v[184:187], v[188:191], a[224:239]
	v_mfma_f32_32x32x16_bf16 a[160:175], v[184:187], v[192:195], a[160:175]
	v_mfma_f32_32x32x16_bf16 a[96:111], v[184:187], v[196:199], a[96:111]
	v_mfma_f32_32x32x16_bf16 a[32:47], v[184:187], v[200:203], a[32:47]
	ds_read_b128 v[184:187], v48 offset:32
	v_lshl_add_u64 v[50:51], v[0:1], 0, s[2:3]
	global_load_dwordx4 v[88:91], v[50:51], off
	v_lshl_add_u64 v[50:51], v[2:3], 0, s[2:3]
	s_or_b32 s2, s34, 0x50000
	global_load_dwordx4 v[92:95], v[50:51], off
	v_lshl_add_u64 v[50:51], v[0:1], 0, s[2:3]
	global_load_dwordx4 v[96:99], v[50:51], off
	v_lshl_add_u64 v[50:51], v[2:3], 0, s[2:3]
	s_or_b32 s2, s34, 0x60000
	global_load_dwordx4 v[108:111], v[50:51], off
	s_waitcnt lgkmcnt(3)
; #define GLOAD(RA, RB, kt) { _Pragma("unroll") for (int i = 0; i < 8; ++i) { const int ia = (tail && i >= 4) ? i - 4 : i; \
;     RA[i] = *(const u32x4*)(abase + ((size_t)(32 * ia) * lda + (kt) * 64) * 2 + aoff); RB[i] = *(const u32x4*)(bbase + ((size_t)(32 * i) * K + (kt) * 64) * 2 + boff); } }
; #define LWRITE(RA, RB, buf) { char* as_ = lds + (buf) * 2 * G_TILE; char* bs_ = as_ + G_TILE; _Pragma("unroll") for (int i = 0; i < 8; ++i) { *(u32x4*)(as_ + (lrow + 32 * i) * GS_B + lch * 16) = RA[i]; *(u32x4*)(bs_ + (lrow + 32 * i) * GS_B + lch * 16) = RB[i]; } }
; template <int EPI>
; DEV void gemm_tile(CParams& p, int layer, const bf16_t* __restrict__ A, int lda, const bf16_t* __restrict__ Bt, int K, int m0, int n0, int nt, char* lds, const int swave) {
;     ...
;   GLOAD(ra0, rb0, 0); GLOAD(ra1, rb1, 1); LWRITE(ra0, rb0, 0); __syncthreads();
; #pragma unroll 1
;   for (int kt = 0; kt < nk; kt += 2) {
;     if (kt + 2 < nk) GLOAD(ra0, rb0, kt + 2);
;     COMPUTE(0, ra1, rb1, 1, true);
	v_mfma_f32_32x32x16_bf16 a[240:255], v[204:207], v[188:191], a[240:255]
	v_mfma_f32_32x32x16_bf16 a[176:191], v[204:207], v[192:195], a[176:191]
	v_mfma_f32_32x32x16_bf16 a[112:127], v[204:207], v[196:199], a[112:127]
	v_mfma_f32_32x32x16_bf16 a[48:63], v[204:207], v[200:203], a[48:63]
	ds_read_b128 v[204:207], v48 offset:4640
	v_lshl_add_u64 v[50:51], v[0:1], 0, s[2:3]
	global_load_dwordx4 v[124:127], v[50:51], off
	v_lshl_add_u64 v[50:51], v[2:3], 0, s[2:3]
	s_or_b32 s34, s34, 0x70000
	global_load_dwordx4 v[144:147], v[50:51], off
	v_lshl_add_u64 v[50:51], v[0:1], 0, s[34:35]
	global_load_dwordx4 v[160:163], v[50:51], off
	v_lshl_add_u64 v[50:51], v[2:3], 0, s[34:35]
	global_load_dwordx4 v[180:183], v[50:51], off
	s_waitcnt vmcnt(31)
	ds_write_b128 v31, v[100:103]
	s_waitcnt vmcnt(30)
	ds_write_b128 v32, v[104:107]
	s_waitcnt vmcnt(29)
	ds_write_b128 v41, v[112:115]
	s_waitcnt vmcnt(28)
	ds_write_b128 v42, v[116:119]
	s_waitcnt lgkmcnt(5)
	v_mfma_f32_32x32x16_bf16 a[192:207], v[184:187], v[208:211], a[192:207]
	v_mfma_f32_32x32x16_bf16 a[128:143], v[184:187], v[212:215], a[128:143]
	v_mfma_f32_32x32x16_bf16 a[64:79], v[184:187], v[216:219], a[64:79]
	v_mfma_f32_32x32x16_bf16 a[0:15], v[184:187], v[220:223], a[0:15]
	ds_read_b128 v[184:187], v48 offset:9248
	ds_read_b128 v[188:191], v49 offset:64
	ds_read_b128 v[192:195], v49 offset:4672
	s_waitcnt lgkmcnt(7)
	v_mfma_f32_32x32x16_bf16 a[208:223], v[204:207], v[208:211], a[208:223]
	v_mfma_f32_32x32x16_bf16 a[144:159], v[204:207], v[212:215], a[144:159]
	v_mfma_f32_32x32x16_bf16 a[80:95], v[204:207], v[216:219], a[80:95]
	v_mfma_f32_32x32x16_bf16 a[16:31], v[204:207], v[220:223], a[16:31]
	ds_read_b128 v[204:207], v48 offset:13856
	ds_read_b128 v[196:199], v49 offset:9280
	ds_read_b128 v[200:203], v49 offset:13888
	s_waitcnt lgkmcnt(5)
	v_mfma_f32_32x32x16_bf16 a[224:239], v[184:187], v[208:211], a[224:239]
	v_mfma_f32_32x32x16_bf16 a[160:175], v[184:187], v[212:215], a[160:175]
	v_mfma_f32_32x32x16_bf16 a[96:111], v[184:187], v[216:219], a[96:111]
	v_mfma_f32_32x32x16_bf16 a[32:47], v[184:187], v[220:223], a[32:47]
	ds_read_b128 v[184:187], v48 offset:64
	s_waitcnt lgkmcnt(3)
	v_mfma_f32_32x32x16_bf16 a[240:255], v[204:207], v[208:211], a[240:255]
	v_mfma_f32_32x32x16_bf16 a[176:191], v[204:207], v[212:215], a[176:191]
	v_mfma_f32_32x32x16_bf16 a[112:127], v[204:207], v[216:219], a[112:127]
	v_mfma_f32_32x32x16_bf16 a[48:63], v[204:207], v[220:223], a[48:63]
	ds_read_b128 v[204:207], v48 offset:4672
	s_waitcnt vmcnt(27)
	ds_write_b128 v37, v[120:123]
	s_waitcnt vmcnt(26)
	ds_write_b128 v38, v[128:131]
	s_waitcnt vmcnt(25)
	ds_write_b128 v39, v[132:135]
	s_waitcnt vmcnt(24)
	ds_write_b128 v40, v[136:139]
	s_waitcnt lgkmcnt(5)
	v_mfma_f32_32x32x16_bf16 a[192:207], v[184:187], v[188:191], a[192:207]
	v_mfma_f32_32x32x16_bf16 a[128:143], v[184:187], v[192:195], a[128:143]
	v_mfma_f32_32x32x16_bf16 a[64:79], v[184:187], v[196:199], a[64:79]
	v_mfma_f32_32x32x16_bf16 a[0:15], v[184:187], v[200:203], a[0:15]
	ds_read_b128 v[184:187], v48 offset:9280
	ds_read_b128 v[208:211], v49 offset:96
	ds_read_b128 v[212:215], v49 offset:4704
	s_waitcnt lgkmcnt(7)
	v_mfma_f32_32x32x16_bf16 a[208:223], v[204:207], v[188:191], a[208:223]
	v_mfma_f32_32x32x16_bf16 a[144:159], v[204:207], v[192:195], a[144:159]
	v_mfma_f32_32x32x16_bf16 a[80:95], v[204:207], v[196:199], a[80:95]
	v_mfma_f32_32x32x16_bf16 a[16:31], v[204:207], v[200:203], a[16:31]
	ds_read_b128 v[204:207], v48 offset:13888
	ds_read_b128 v[216:219], v49 offset:9312
	ds_read_b128 v[220:223], v49 offset:13920
	s_waitcnt lgkmcnt(5)
	v_mfma_f32_32x32x16_bf16 a[224:239], v[184:187], v[188:191], a[224:239]
	v_mfma_f32_32x32x16_bf16 a[160:175], v[184:187], v[192:195], a[160:175]
	v_mfma_f32_32x32x16_bf16 a[96:111], v[184:187], v[196:199], a[96:111]
	v_mfma_f32_32x32x16_bf16 a[32:47], v[184:187], v[200:203], a[32:47]
	ds_read_b128 v[184:187], v48 offset:96
	s_waitcnt lgkmcnt(3)
	v_mfma_f32_32x32x16_bf16 a[240:255], v[204:207], v[188:191], a[240:255]
	v_mfma_f32_32x32x16_bf16 a[176:191], v[204:207], v[192:195], a[176:191]
	v_mfma_f32_32x32x16_bf16 a[112:127], v[204:207], v[196:199], a[112:127]
	v_mfma_f32_32x32x16_bf16 a[48:63], v[204:207], v[200:203], a[48:63]
	ds_read_b128 v[204:207], v48 offset:4704
	s_waitcnt vmcnt(23)
	ds_write_b128 v33, v[140:143]
	s_waitcnt vmcnt(22)
	ds_write_b128 v34, v[148:151]
	s_waitcnt vmcnt(21)
	ds_write_b128 v35, v[152:155]
	s_waitcnt vmcnt(20)
	ds_write_b128 v36, v[156:159]
	s_waitcnt lgkmcnt(5)
	v_mfma_f32_32x32x16_bf16 a[192:207], v[184:187], v[208:211], a[192:207]
	v_mfma_f32_32x32x16_bf16 a[128:143], v[184:187], v[212:215], a[128:143]
	v_mfma_f32_32x32x16_bf16 a[64:79], v[184:187], v[216:219], a[64:79]
	v_mfma_f32_32x32x16_bf16 a[0:15], v[184:187], v[220:223], a[0:15]
	ds_read_b128 v[184:187], v48 offset:9312
	s_waitcnt lgkmcnt(5)
	v_mfma_f32_32x32x16_bf16 a[208:223], v[204:207], v[208:211], a[208:223]
	v_mfma_f32_32x32x16_bf16 a[144:159], v[204:207], v[212:215], a[144:159]
	v_mfma_f32_32x32x16_bf16 a[80:95], v[204:207], v[216:219], a[80:95]
	v_mfma_f32_32x32x16_bf16 a[16:31], v[204:207], v[220:223], a[16:31]
	ds_read_b128 v[204:207], v48 offset:13920
	s_waitcnt lgkmcnt(1)
	v_mfma_f32_32x32x16_bf16 a[224:239], v[184:187], v[208:211], a[224:239]
	v_mfma_f32_32x32x16_bf16 a[160:175], v[184:187], v[212:215], a[160:175]
	v_mfma_f32_32x32x16_bf16 a[96:111], v[184:187], v[216:219], a[96:111]
	v_mfma_f32_32x32x16_bf16 a[32:47], v[184:187], v[220:223], a[32:47]
	s_waitcnt lgkmcnt(0)
	v_mfma_f32_32x32x16_bf16 a[240:255], v[204:207], v[208:211], a[240:255]
	v_mfma_f32_32x32x16_bf16 a[176:191], v[204:207], v[212:215], a[176:191]
	v_mfma_f32_32x32x16_bf16 a[112:127], v[204:207], v[216:219], a[112:127]
	v_mfma_f32_32x32x16_bf16 a[48:63], v[204:207], v[220:223], a[48:63]
	s_waitcnt vmcnt(19)
	ds_write_b128 v43, v[164:167]
	s_waitcnt vmcnt(18)
	ds_write_b128 v44, v[168:171]
	s_waitcnt vmcnt(17)
	ds_write_b128 v45, v[172:175]
	s_waitcnt vmcnt(16)
	ds_write_b128 v46, v[176:179]

; #define GLOAD(RA, RB, kt) { _Pragma("unroll") for (int i = 0; i < 8; ++i) { const int ia = (tail && i >= 4) ? i - 4 : i; \
;     RA[i] = *(const u32x4*)(abase + ((size_t)(32 * ia) * lda + (kt) * 64) * 2 + aoff); RB[i] = *(const u32x4*)(bbase + ((size_t)(32 * i) * K + (kt) * 64) * 2 + boff); } }
; #define LWRITE(RA, RB, buf) { char* as_ = lds + (buf) * 2 * G_TILE; char* bs_ = as_ + G_TILE; _Pragma("unroll") for (int i = 0; i < 8; ++i) { *(u32x4*)(as_ + (lrow + 32 * i) * GS_B + lch * 16) = RA[i]; *(u32x4*)(bs_ + (lrow + 32 * i) * GS_B + lch * 16) = RB[i]; } }
; template <int EPI>
; DEV void gemm_tile(CParams& p, int layer, const bf16_t* __restrict__ A, int lda, const bf16_t* __restrict__ Bt, int K, int m0, int n0, int nt, char* lds, const int swave) {
;     ...
;   GLOAD(ra0, rb0, 0); GLOAD(ra1, rb1, 1); LWRITE(ra0, rb0, 0); __syncthreads();
; #pragma unroll 1
;   for (int kt = 0; kt < nk; kt += 2) {
;     if (kt + 2 < nk) GLOAD(ra0, rb0, kt + 2);
;     COMPUTE(0, ra1, rb1, 1, true);
;     __syncthreads();
;     const bool more = kt + 2 < nk;
;     if (kt + 3 < nk) GLOAD(ra1, rb1, kt + 3);
;     COMPUTE(1, ra0, rb0, 0, more);
.LBB0_119:
	v_add_u32_e32 v224, 0x1b000, v29
	v_add_u32_e32 v225, 0x12000, v49
	s_andn2_b64 vcc, exec, s[60:61]
	s_cbranch_vccnz .Lpg_i1_nomore
	ds_read_b128 v[188:191], v225
	ds_read_b128 v[192:195], v225 offset:4608
	ds_read_b128 v[196:199], v225 offset:9216
	ds_read_b128 v[200:203], v225 offset:13824
	ds_read_b128 v[184:187], v224
	ds_read_b128 v[204:207], v224 offset:4608
	s_waitcnt lgkmcnt(1)
	v_mfma_f32_32x32x16_bf16 a[192:207], v[184:187], v[188:191], a[192:207]
	v_mfma_f32_32x32x16_bf16 a[128:143], v[184:187], v[192:195], a[128:143]
	v_mfma_f32_32x32x16_bf16 a[64:79], v[184:187], v[196:199], a[64:79]
	v_mfma_f32_32x32x16_bf16 a[0:15], v[184:187], v[200:203], a[0:15]
	ds_read_b128 v[184:187], v224 offset:9216
	ds_read_b128 v[208:211], v225 offset:32
	ds_read_b128 v[212:215], v225 offset:4640
	s_lshl_b32 s34, s36, 7
	v_lshl_add_u64 v[50:51], v[0:1], 0, s[34:35]
	v_lshl_add_u64 v[64:65], v[2:3], 0, s[34:35]
	global_load_dwordx4 v[100:103], v[50:51], off offset:384
	global_load_dwordx4 v[104:107], v[64:65], off offset:384
	v_add_co_u32_e32 v50, vcc, 0x10000, v50
	s_nop 1
	v_addc_co_u32_e32 v51, vcc, 0, v51, vcc
	v_add_co_u32_e32 v64, vcc, 0x10000, v64
	s_nop 1
	v_addc_co_u32_e32 v65, vcc, 0, v65, vcc
	global_load_dwordx4 v[112:115], v[50:51], off offset:384
	global_load_dwordx4 v[116:119], v[64:65], off offset:384
	s_waitcnt lgkmcnt(3)
	v_mfma_f32_32x32x16_bf16 a[208:223], v[204:207], v[188:191], a[208:223]
	v_mfma_f32_32x32x16_bf16 a[144:159], v[204:207], v[192:195], a[144:159]
	v_mfma_f32_32x32x16_bf16 a[80:95], v[204:207], v[196:199], a[80:95]
	v_mfma_f32_32x32x16_bf16 a[16:31], v[204:207], v[200:203], a[16:31]
	ds_read_b128 v[204:207], v224 offset:13824
	ds_read_b128 v[216:219], v225 offset:9248
	ds_read_b128 v[220:223], v225 offset:13856
	v_lshl_add_u64 v[50:51], v[4:5], 0, s[34:35]
	v_lshl_add_u64 v[64:65], v[6:7], 0, s[34:35]
	global_load_dwordx4 v[120:123], v[50:51], off offset:384
	global_load_dwordx4 v[128:131], v[64:65], off offset:384
	v_lshl_add_u64 v[50:51], v[8:9], 0, s[34:35]
	v_lshl_add_u64 v[64:65], v[10:11], 0, s[34:35]
	global_load_dwordx4 v[132:135], v[50:51], off offset:384
	global_load_dwordx4 v[136:139], v[64:65], off offset:384
	s_waitcnt lgkmcnt(5)
	v_mfma_f32_32x32x16_bf16 a[224:239], v[184:187], v[188:191], a[224:239]
	v_mfma_f32_32x32x16_bf16 a[160:175], v[184:187], v[192:195], a[160:175]
	v_mfma_f32_32x32x16_bf16 a[96:111], v[184:187], v[196:199], a[96:111]
	v_mfma_f32_32x32x16_bf16 a[32:47], v[184:187], v[200:203], a[32:47]
	ds_read_b128 v[184:187], v224 offset:32
	v_lshl_add_u64 v[50:51], v[12:13], 0, s[34:35]
	v_lshl_add_u64 v[64:65], v[14:15], 0, s[34:35]
	global_load_dwordx4 v[140:143], v[50:51], off offset:384
	global_load_dwordx4 v[148:151], v[64:65], off offset:384
	v_lshl_add_u64 v[50:51], v[16:17], 0, s[34:35]
	v_lshl_add_u64 v[64:65], v[18:19], 0, s[34:35]
	global_load_dwordx4 v[152:155], v[50:51], off offset:384
	global_load_dwordx4 v[156:159], v[64:65], off offset:384
	s_waitcnt lgkmcnt(3)
	v_mfma_f32_32x32x16_bf16 a[240:255], v[204:207], v[188:191], a[240:255]
	v_mfma_f32_32x32x16_bf16 a[176:191], v[204:207], v[192:195], a[176:191]
	v_mfma_f32_32x32x16_bf16 a[112:127], v[204:207], v[196:199], a[112:127]
	v_mfma_f32_32x32x16_bf16 a[48:63], v[204:207], v[200:203], a[48:63]
	ds_read_b128 v[204:207], v224 offset:4640
	v_lshl_add_u64 v[50:51], v[20:21], 0, s[34:35]
	v_lshl_add_u64 v[64:65], v[22:23], 0, s[34:35]
	global_load_dwordx4 v[164:167], v[50:51], off offset:384
	global_load_dwordx4 v[168:171], v[64:65], off offset:384
	v_lshl_add_u64 v[50:51], v[24:25], 0, s[34:35]
	v_lshl_add_u64 v[64:65], v[26:27], 0, s[34:35]
	global_load_dwordx4 v[172:175], v[50:51], off offset:384
	global_load_dwordx4 v[176:179], v[64:65], off offset:384
	s_waitcnt vmcnt(31)
	ds_write_b128 v30, v[52:55]
	s_waitcnt vmcnt(30)
	ds_write_b128 v30, v[56:59] offset:36864
	s_waitcnt vmcnt(29)
	ds_write_b128 v30, v[60:63] offset:4608
	s_waitcnt vmcnt(28)
	ds_write_b128 v30, v[68:71] offset:41472
	s_waitcnt lgkmcnt(5)
	v_mfma_f32_32x32x16_bf16 a[192:207], v[184:187], v[208:211], a[192:207]
	v_mfma_f32_32x32x16_bf16 a[128:143], v[184:187], v[212:215], a[128:143]
	v_mfma_f32_32x32x16_bf16 a[64:79], v[184:187], v[216:219], a[64:79]
	v_mfma_f32_32x32x16_bf16 a[0:15], v[184:187], v[220:223], a[0:15]
	ds_read_b128 v[184:187], v224 offset:9248
	ds_read_b128 v[188:191], v225 offset:64
	ds_read_b128 v[192:195], v225 offset:4672
	s_waitcnt lgkmcnt(7)
; #define GLOAD(RA, RB, kt) { _Pragma("unroll") for (int i = 0; i < 8; ++i) { const int ia = (tail && i >= 4) ? i - 4 : i; \
;     RA[i] = *(const u32x4*)(abase + ((size_t)(32 * ia) * lda + (kt) * 64) * 2 + aoff); RB[i] = *(const u32x4*)(bbase + ((size_t)(32 * i) * K + (kt) * 64) * 2 + boff); } }
; #define LWRITE(RA, RB, buf) { char* as_ = lds + (buf) * 2 * G_TILE; char* bs_ = as_ + G_TILE; _Pragma("unroll") for (int i = 0; i < 8; ++i) { *(u32x4*)(as_ + (lrow + 32 * i) * GS_B + lch * 16) = RA[i]; *(u32x4*)(bs_ + (lrow + 32 * i) * GS_B + lch * 16) = RB[i]; } }
; template <int EPI>
; DEV void gemm_tile(CParams& p, int layer, const bf16_t* __restrict__ A, int lda, const bf16_t* __restrict__ Bt, int K, int m0, int n0, int nt, char* lds, const int swave) {
;     ...
;   GLOAD(ra0, rb0, 0); GLOAD(ra1, rb1, 1); LWRITE(ra0, rb0, 0); __syncthreads();
; #pragma unroll 1
;   for (int kt = 0; kt < nk; kt += 2) {
;     if (kt + 2 < nk) GLOAD(ra0, rb0, kt + 2);
;     COMPUTE(0, ra1, rb1, 1, true);
	v_mfma_f32_32x32x16_bf16 a[208:223], v[204:207], v[208:211], a[208:223]
	v_mfma_f32_32x32x16_bf16 a[144:159], v[204:207], v[212:215], a[144:159]
	v_mfma_f32_32x32x16_bf16 a[80:95], v[204:207], v[216:219], a[80:95]
	v_mfma_f32_32x32x16_bf16 a[16:31], v[204:207], v[220:223], a[16:31]
	ds_read_b128 v[204:207], v224 offset:13856
	ds_read_b128 v[196:199], v225 offset:9280
	ds_read_b128 v[200:203], v225 offset:13888
	s_waitcnt lgkmcnt(5)
	v_mfma_f32_32x32x16_bf16 a[224:239], v[184:187], v[208:211], a[224:239]
	v_mfma_f32_32x32x16_bf16 a[160:175], v[184:187], v[212:215], a[160:175]
	v_mfma_f32_32x32x16_bf16 a[96:111], v[184:187], v[216:219], a[96:111]
	v_mfma_f32_32x32x16_bf16 a[32:47], v[184:187], v[220:223], a[32:47]
	ds_read_b128 v[184:187], v224 offset:64
	s_waitcnt lgkmcnt(3)
	v_mfma_f32_32x32x16_bf16 a[240:255], v[204:207], v[208:211], a[240:255]
	v_mfma_f32_32x32x16_bf16 a[176:191], v[204:207], v[212:215], a[176:191]
	v_mfma_f32_32x32x16_bf16 a[112:127], v[204:207], v[216:219], a[112:127]
	v_mfma_f32_32x32x16_bf16 a[48:63], v[204:207], v[220:223], a[48:63]
	ds_read_b128 v[204:207], v224 offset:4672
	s_waitcnt vmcnt(27)
	ds_write_b128 v30, v[72:75] offset:9216
	s_waitcnt vmcnt(26)
	ds_write_b128 v30, v[76:79] offset:46080
	s_waitcnt vmcnt(25)
	ds_write_b128 v30, v[80:83] offset:13824
	s_waitcnt vmcnt(24)
	ds_write_b128 v30, v[84:87] offset:50688
	s_waitcnt lgkmcnt(5)
	v_mfma_f32_32x32x16_bf16 a[192:207], v[184:187], v[188:191], a[192:207]
	v_mfma_f32_32x32x16_bf16 a[128:143], v[184:187], v[192:195], a[128:143]
	v_mfma_f32_32x32x16_bf16 a[64:79], v[184:187], v[196:199], a[64:79]
	v_mfma_f32_32x32x16_bf16 a[0:15], v[184:187], v[200:203], a[0:15]
	ds_read_b128 v[184:187], v224 offset:9280
	ds_read_b128 v[208:211], v225 offset:96
	ds_read_b128 v[212:215], v225 offset:4704
	s_waitcnt lgkmcnt(7)
	v_mfma_f32_32x32x16_bf16 a[208:223], v[204:207], v[188:191], a[208:223]
	v_mfma_f32_32x32x16_bf16 a[144:159], v[204:207], v[192:195], a[144:159]
	v_mfma_f32_32x32x16_bf16 a[80:95], v[204:207], v[196:199], a[80:95]
	v_mfma_f32_32x32x16_bf16 a[16:31], v[204:207], v[200:203], a[16:31]
	ds_read_b128 v[204:207], v224 offset:13888
	ds_read_b128 v[216:219], v225 offset:9312
	ds_read_b128 v[220:223], v225 offset:13920
	s_waitcnt lgkmcnt(5)
	v_mfma_f32_32x32x16_bf16 a[224:239], v[184:187], v[188:191], a[224:239]
	v_mfma_f32_32x32x16_bf16 a[160:175], v[184:187], v[192:195], a[160:175]
	v_mfma_f32_32x32x16_bf16 a[96:111], v[184:187], v[196:199], a[96:111]
	v_mfma_f32_32x32x16_bf16 a[32:47], v[184:187], v[200:203], a[32:47]
	ds_read_b128 v[184:187], v224 offset:96
	s_waitcnt lgkmcnt(3)
	v_mfma_f32_32x32x16_bf16 a[240:255], v[204:207], v[188:191], a[240:255]
	v_mfma_f32_32x32x16_bf16 a[176:191], v[204:207], v[192:195], a[176:191]
	v_mfma_f32_32x32x16_bf16 a[112:127], v[204:207], v[196:199], a[112:127]
	v_mfma_f32_32x32x16_bf16 a[48:63], v[204:207], v[200:203], a[48:63]
	ds_read_b128 v[204:207], v224 offset:4704
	s_waitcnt vmcnt(23)
	ds_write_b128 v30, v[88:91] offset:18432
	s_waitcnt vmcnt(22)
	ds_write_b128 v30, v[92:95] offset:55296
	s_waitcnt vmcnt(21)
	ds_write_b128 v30, v[96:99] offset:23040
	s_waitcnt vmcnt(20)
	ds_write_b128 v30, v[108:111] offset:59904
	s_waitcnt lgkmcnt(5)
	v_mfma_f32_32x32x16_bf16 a[192:207], v[184:187], v[208:211], a[192:207]
	v_mfma_f32_32x32x16_bf16 a[128:143], v[184:187], v[212:215], a[128:143]
	v_mfma_f32_32x32x16_bf16 a[64:79], v[184:187], v[216:219], a[64:79]
	v_mfma_f32_32x32x16_bf16 a[0:15], v[184:187], v[220:223], a[0:15]
	ds_read_b128 v[184:187], v224 offset:9312
	s_waitcnt lgkmcnt(5)
	v_mfma_f32_32x32x16_bf16 a[208:223], v[204:207], v[208:211], a[208:223]
	v_mfma_f32_32x32x16_bf16 a[144:159], v[204:207], v[212:215], a[144:159]
	v_mfma_f32_32x32x16_bf16 a[80:95], v[204:207], v[216:219], a[80:95]
	v_mfma_f32_32x32x16_bf16 a[16:31], v[204:207], v[220:223], a[16:31]
	ds_read_b128 v[204:207], v224 offset:13920
	s_waitcnt lgkmcnt(1)
	v_mfma_f32_32x32x16_bf16 a[224:239], v[184:187], v[208:211], a[224:239]
	v_mfma_f32_32x32x16_bf16 a[160:175], v[184:187], v[212:215], a[160:175]
	v_mfma_f32_32x32x16_bf16 a[96:111], v[184:187], v[216:219], a[96:111]
	v_mfma_f32_32x32x16_bf16 a[32:47], v[184:187], v[220:223], a[32:47]
	s_waitcnt lgkmcnt(0)
	v_mfma_f32_32x32x16_bf16 a[240:255], v[204:207], v[208:211], a[240:255]
	v_mfma_f32_32x32x16_bf16 a[176:191], v[204:207], v[212:215], a[176:191]
	v_mfma_f32_32x32x16_bf16 a[112:127], v[204:207], v[216:219], a[112:127]
	v_mfma_f32_32x32x16_bf16 a[48:63], v[204:207], v[220:223], a[48:63]
	s_waitcnt vmcnt(19)
	ds_write_b128 v30, v[124:127] offset:27648
	s_waitcnt vmcnt(18)
	ds_write_b128 v30, v[144:147] offset:64512
	s_waitcnt vmcnt(17)
	ds_write_b128 v30, v[160:163] offset:32256
	s_waitcnt vmcnt(16)
	ds_write_b128 v47, v[180:183]
	s_branch .LBB0_98

; #define GLOAD(RA, RB, kt) { _Pragma("unroll") for (int i = 0; i < 8; ++i) { const int ia = (tail && i >= 4) ? i - 4 : i; \
;     RA[i] = *(const u32x4*)(abase + ((size_t)(32 * ia) * lda + (kt) * 64) * 2 + aoff); RB[i] = *(const u32x4*)(bbase + ((size_t)(32 * i) * K + (kt) * 64) * 2 + boff); } }
; #define LWRITE(RA, RB, buf) { char* as_ = lds + (buf) * 2 * G_TILE; char* bs_ = as_ + G_TILE; _Pragma("unroll") for (int i = 0; i < 8; ++i) { *(u32x4*)(as_ + (lrow + 32 * i) * GS_B + lch * 16) = RA[i]; *(u32x4*)(bs_ + (lrow + 32 * i) * GS_B + lch * 16) = RB[i]; } }
; template <int EPI>
; DEV void gemm_tile(CParams& p, int layer, const bf16_t* __restrict__ A, int lda, const bf16_t* __restrict__ Bt, int K, int m0, int n0, int nt, char* lds, const int swave) {
;     ...
;   const char* asr = lds + (wm * 128 + lr) * GS_B + hh * 16;
;   const char* bsr = lds + G_TILE + (wn * 128 + lr) * GS_B + hh * 16;
;   char* wsw = lds + lrow * GS_B + lch * 16;
;     ...
;   GLOAD(ra0, rb0, 0); GLOAD(ra1, rb1, 1); LWRITE(ra0, rb0, 0); __syncthreads();
; #pragma unroll 1
;   for (int kt = 0; kt < nk; kt += 2) {
;     if (kt + 2 < nk) GLOAD(ra0, rb0, kt + 2);
;     COMPUTE(0, ra1, rb1, 1, true);
;     __syncthreads();
.LBB0_161:
	s_cmp_eq_u32 s86, 0
	s_cbranch_scc0 .Lzi_i2
	ds_read_b128 v[164:167], v26
	ds_read_b128 v[168:171], v26 offset:4608
	ds_read_b128 v[172:175], v26 offset:9216
	ds_read_b128 v[176:179], v26 offset:13824
	ds_read_b128 v[160:163], v25
	ds_read_b128 v[180:183], v25 offset:4608
	s_waitcnt lgkmcnt(1)
	v_mfma_f32_32x32x16_bf16 a[96:111], v[160:163], v[164:167], 0
	v_mfma_f32_32x32x16_bf16 a[0:15], v[160:163], v[168:171], 0
	v_mfma_f32_32x32x16_bf16 a[16:31], v[160:163], v[172:175], 0
	v_mfma_f32_32x32x16_bf16 a[32:47], v[160:163], v[176:179], 0
	ds_read_b128 v[160:163], v25 offset:9216
	ds_read_b128 v[184:187], v26 offset:32
	ds_read_b128 v[188:191], v26 offset:4640
	v_lshl_add_u64 v[28:29], v[2:3], 0, s[34:35]
	v_lshl_add_u64 v[30:31], v[4:5], 0, s[34:35]
	s_add_i32 s2, s100, s28
	s_lshl_b32 s44, s100, 6
	global_load_dwordx4 v[32:35], v[28:29], off
	global_load_dwordx4 v[36:39], v[30:31], off
	v_lshl_add_u64 v[28:29], v[28:29], 0, s[8:9]
	v_lshl_add_u64 v[30:31], v[30:31], 0, s[8:9]
	s_lshl_b32 s2, s2, 7
	s_mov_b32 s3, s35
	global_load_dwordx4 v[40:43], v[28:29], off
	global_load_dwordx4 v[44:47], v[30:31], off
	s_waitcnt lgkmcnt(3)
	v_mfma_f32_32x32x16_bf16 a[80:95], v[180:183], v[164:167], 0
	v_mfma_f32_32x32x16_bf16 a[48:63], v[180:183], v[168:171], 0
	v_mfma_f32_32x32x16_bf16 a[64:79], v[180:183], v[172:175], 0
	v_mfma_f32_32x32x16_bf16 a[112:127], v[180:183], v[176:179], 0
	ds_read_b128 v[180:183], v25 offset:13824
	ds_read_b128 v[192:195], v26 offset:9248
	ds_read_b128 v[196:199], v26 offset:13856
	v_lshl_add_u64 v[28:29], v[2:3], 0, s[2:3]
	v_lshl_add_u64 v[30:31], v[4:5], 0, s[2:3]
	s_add_i32 s2, s44, s38
	s_lshl_b32 s2, s2, 1
	global_load_dwordx4 v[48:51], v[28:29], off
	global_load_dwordx4 v[52:55], v[30:31], off
	v_lshl_add_u64 v[28:29], v[2:3], 0, s[2:3]
	v_lshl_add_u64 v[30:31], v[4:5], 0, s[2:3]
	s_add_i32 s34, s34, s91
	s_add_i32 s2, s44, s39
	global_load_dwordx4 v[56:59], v[28:29], off
	global_load_dwordx4 v[60:63], v[30:31], off
	s_waitcnt lgkmcnt(5)
	v_mfma_f32_32x32x16_bf16 a[128:143], v[160:163], v[164:167], 0
	v_mfma_f32_32x32x16_bf16 a[144:159], v[160:163], v[168:171], 0
	v_mfma_f32_32x32x16_bf16 a[160:175], v[160:163], v[172:175], 0
	v_mfma_f32_32x32x16_bf16 a[176:191], v[160:163], v[176:179], 0
	ds_read_b128 v[160:163], v25 offset:32
	v_lshl_add_u64 v[28:29], v[2:3], 0, s[34:35]
	v_lshl_add_u64 v[30:31], v[4:5], 0, s[34:35]
	s_lshl_b32 s34, s2, 1
	s_add_i32 s2, s44, s68
	global_load_dwordx4 v[64:67], v[28:29], off
	global_load_dwordx4 v[68:71], v[30:31], off
	v_lshl_add_u64 v[28:29], v[2:3], 0, s[34:35]
	v_lshl_add_u64 v[30:31], v[4:5], 0, s[34:35]
	s_lshl_b32 s34, s2, 1
	s_add_i32 s44, s44, s40
	global_load_dwordx4 v[72:75], v[28:29], off
	global_load_dwordx4 v[76:79], v[30:31], off
	s_waitcnt lgkmcnt(3)
	v_mfma_f32_32x32x16_bf16 a[192:207], v[180:183], v[164:167], 0
	v_mfma_f32_32x32x16_bf16 a[208:223], v[180:183], v[168:171], 0
	v_mfma_f32_32x32x16_bf16 a[224:239], v[180:183], v[172:175], 0
	v_mfma_f32_32x32x16_bf16 a[240:255], v[180:183], v[176:179], 0
	ds_read_b128 v[180:183], v25 offset:4640
	v_lshl_add_u64 v[28:29], v[2:3], 0, s[34:35]
	v_lshl_add_u64 v[30:31], v[4:5], 0, s[34:35]
	s_lshl_b32 s34, s44, 1
	global_load_dwordx4 v[80:83], v[28:29], off
	global_load_dwordx4 v[92:95], v[30:31], off
	v_lshl_add_u64 v[28:29], v[2:3], 0, s[34:35]
	v_lshl_add_u64 v[30:31], v[4:5], 0, s[34:35]
	global_load_dwordx4 v[100:103], v[28:29], off
	global_load_dwordx4 v[108:111], v[30:31], off
	s_waitcnt vmcnt(31)
	ds_write_b128 v8, v[84:87]
	s_waitcnt vmcnt(30)
	ds_write_b128 v9, v[88:91]
	s_waitcnt vmcnt(29)
	ds_write_b128 v18, v[96:99]
	s_waitcnt vmcnt(28)
	ds_write_b128 v19, v[104:107]
	s_waitcnt lgkmcnt(5)
	v_mfma_f32_32x32x16_bf16 a[96:111], v[160:163], v[184:187], a[96:111]
	v_mfma_f32_32x32x16_bf16 a[0:15], v[160:163], v[188:191], a[0:15]
	v_mfma_f32_32x32x16_bf16 a[16:31], v[160:163], v[192:195], a[16:31]
	v_mfma_f32_32x32x16_bf16 a[32:47], v[160:163], v[196:199], a[32:47]
	ds_read_b128 v[160:163], v25 offset:9248
	ds_read_b128 v[164:167], v26 offset:64
	ds_read_b128 v[168:171], v26 offset:4672
	s_waitcnt lgkmcnt(7)
	v_mfma_f32_32x32x16_bf16 a[80:95], v[180:183], v[184:187], a[80:95]
	v_mfma_f32_32x32x16_bf16 a[48:63], v[180:183], v[188:191], a[48:63]
	v_mfma_f32_32x32x16_bf16 a[64:79], v[180:183], v[192:195], a[64:79]
	v_mfma_f32_32x32x16_bf16 a[112:127], v[180:183], v[196:199], a[112:127]
	ds_read_b128 v[180:183], v25 offset:13856
	ds_read_b128 v[172:175], v26 offset:9280
	ds_read_b128 v[176:179], v26 offset:13888
	s_waitcnt lgkmcnt(5)
	v_mfma_f32_32x32x16_bf16 a[128:143], v[160:163], v[184:187], a[128:143]
	v_mfma_f32_32x32x16_bf16 a[144:159], v[160:163], v[188:191], a[144:159]
	v_mfma_f32_32x32x16_bf16 a[160:175], v[160:163], v[192:195], a[160:175]
	v_mfma_f32_32x32x16_bf16 a[176:191], v[160:163], v[196:199], a[176:191]
	ds_read_b128 v[160:163], v25 offset:64
	s_waitcnt lgkmcnt(3)
	v_mfma_f32_32x32x16_bf16 a[192:207], v[180:183], v[184:187], a[192:207]
	v_mfma_f32_32x32x16_bf16 a[208:223], v[180:183], v[188:191], a[208:223]
	v_mfma_f32_32x32x16_bf16 a[224:239], v[180:183], v[192:195], a[224:239]
	v_mfma_f32_32x32x16_bf16 a[240:255], v[180:183], v[196:199], a[240:255]
	ds_read_b128 v[180:183], v25 offset:4672
	s_waitcnt vmcnt(27)
	ds_write_b128 v14, v[112:115]
	s_waitcnt vmcnt(26)
	ds_write_b128 v15, v[116:119]
	s_waitcnt vmcnt(25)
	ds_write_b128 v16, v[120:123]
	s_waitcnt vmcnt(24)
	ds_write_b128 v17, v[124:127]
	s_waitcnt lgkmcnt(5)
; #define GLOAD(RA, RB, kt) { _Pragma("unroll") for (int i = 0; i < 8; ++i) { const int ia = (tail && i >= 4) ? i - 4 : i; \
;     RA[i] = *(const u32x4*)(abase + ((size_t)(32 * ia) * lda + (kt) * 64) * 2 + aoff); RB[i] = *(const u32x4*)(bbase + ((size_t)(32 * i) * K + (kt) * 64) * 2 + boff); } }
; #define LWRITE(RA, RB, buf) { char* as_ = lds + (buf) * 2 * G_TILE; char* bs_ = as_ + G_TILE; _Pragma("unroll") for (int i = 0; i < 8; ++i) { *(u32x4*)(as_ + (lrow + 32 * i) * GS_B + lch * 16) = RA[i]; *(u32x4*)(bs_ + (lrow + 32 * i) * GS_B + lch * 16) = RB[i]; } }
; template <int EPI>
; DEV void gemm_tile(CParams& p, int layer, const bf16_t* __restrict__ A, int lda, const bf16_t* __restrict__ Bt, int K, int m0, int n0, int nt, char* lds, const int swave) {
;     ...
;   GLOAD(ra0, rb0, 0); GLOAD(ra1, rb1, 1); LWRITE(ra0, rb0, 0); __syncthreads();
; #pragma unroll 1
;   for (int kt = 0; kt < nk; kt += 2) {
;     if (kt + 2 < nk) GLOAD(ra0, rb0, kt + 2);
;     COMPUTE(0, ra1, rb1, 1, true);
;     __syncthreads();
	v_mfma_f32_32x32x16_bf16 a[96:111], v[160:163], v[164:167], a[96:111]
	v_mfma_f32_32x32x16_bf16 a[0:15], v[160:163], v[168:171], a[0:15]
	v_mfma_f32_32x32x16_bf16 a[16:31], v[160:163], v[172:175], a[16:31]
	v_mfma_f32_32x32x16_bf16 a[32:47], v[160:163], v[176:179], a[32:47]
	ds_read_b128 v[160:163], v25 offset:9280
	ds_read_b128 v[184:187], v26 offset:96
	ds_read_b128 v[188:191], v26 offset:4704
	s_waitcnt lgkmcnt(7)
	v_mfma_f32_32x32x16_bf16 a[80:95], v[180:183], v[164:167], a[80:95]
	v_mfma_f32_32x32x16_bf16 a[48:63], v[180:183], v[168:171], a[48:63]
	v_mfma_f32_32x32x16_bf16 a[64:79], v[180:183], v[172:175], a[64:79]
	v_mfma_f32_32x32x16_bf16 a[112:127], v[180:183], v[176:179], a[112:127]
	ds_read_b128 v[180:183], v25 offset:13888
	ds_read_b128 v[192:195], v26 offset:9312
	ds_read_b128 v[196:199], v26 offset:13920
	s_waitcnt lgkmcnt(5)
	v_mfma_f32_32x32x16_bf16 a[128:143], v[160:163], v[164:167], a[128:143]
	v_mfma_f32_32x32x16_bf16 a[144:159], v[160:163], v[168:171], a[144:159]
	v_mfma_f32_32x32x16_bf16 a[160:175], v[160:163], v[172:175], a[160:175]
	v_mfma_f32_32x32x16_bf16 a[176:191], v[160:163], v[176:179], a[176:191]
	ds_read_b128 v[160:163], v25 offset:96
	s_waitcnt lgkmcnt(3)
	v_mfma_f32_32x32x16_bf16 a[192:207], v[180:183], v[164:167], a[192:207]
	v_mfma_f32_32x32x16_bf16 a[208:223], v[180:183], v[168:171], a[208:223]
	v_mfma_f32_32x32x16_bf16 a[224:239], v[180:183], v[172:175], a[224:239]
	v_mfma_f32_32x32x16_bf16 a[240:255], v[180:183], v[176:179], a[240:255]
	ds_read_b128 v[180:183], v25 offset:4704
	s_waitcnt vmcnt(23)
	ds_write_b128 v10, v[128:131]
	s_waitcnt vmcnt(22)
	ds_write_b128 v11, v[132:135]
	s_waitcnt vmcnt(21)
	ds_write_b128 v12, v[136:139]
	s_waitcnt vmcnt(20)
	ds_write_b128 v13, v[140:143]
	s_waitcnt lgkmcnt(5)
	v_mfma_f32_32x32x16_bf16 a[96:111], v[160:163], v[184:187], a[96:111]
	v_mfma_f32_32x32x16_bf16 a[0:15], v[160:163], v[188:191], a[0:15]
	v_mfma_f32_32x32x16_bf16 a[16:31], v[160:163], v[192:195], a[16:31]
	v_mfma_f32_32x32x16_bf16 a[32:47], v[160:163], v[196:199], a[32:47]
	ds_read_b128 v[160:163], v25 offset:9312
	s_waitcnt lgkmcnt(5)
	v_mfma_f32_32x32x16_bf16 a[80:95], v[180:183], v[184:187], a[80:95]
	v_mfma_f32_32x32x16_bf16 a[48:63], v[180:183], v[188:191], a[48:63]
	v_mfma_f32_32x32x16_bf16 a[64:79], v[180:183], v[192:195], a[64:79]
	v_mfma_f32_32x32x16_bf16 a[112:127], v[180:183], v[196:199], a[112:127]
	ds_read_b128 v[180:183], v25 offset:13920
	s_waitcnt lgkmcnt(1)
	v_mfma_f32_32x32x16_bf16 a[128:143], v[160:163], v[184:187], a[128:143]
	v_mfma_f32_32x32x16_bf16 a[144:159], v[160:163], v[188:191], a[144:159]
	v_mfma_f32_32x32x16_bf16 a[160:175], v[160:163], v[192:195], a[160:175]
	v_mfma_f32_32x32x16_bf16 a[176:191], v[160:163], v[196:199], a[176:191]
	s_waitcnt lgkmcnt(0)
	v_mfma_f32_32x32x16_bf16 a[192:207], v[180:183], v[184:187], a[192:207]
	v_mfma_f32_32x32x16_bf16 a[208:223], v[180:183], v[188:191], a[208:223]
	v_mfma_f32_32x32x16_bf16 a[224:239], v[180:183], v[192:195], a[224:239]
	v_mfma_f32_32x32x16_bf16 a[240:255], v[180:183], v[196:199], a[240:255]
	s_waitcnt vmcnt(19)
	ds_write_b128 v20, v[144:147]
	s_waitcnt vmcnt(18)
	ds_write_b128 v21, v[148:151]
	s_waitcnt vmcnt(17)
	ds_write_b128 v22, v[152:155]
	s_waitcnt vmcnt(16)
	ds_write_b128 v23, v[156:159]
	s_branch .LBB0_177
.Lzi_i2:
	ds_read_b128 v[164:167], v26
	ds_read_b128 v[168:171], v26 offset:4608
	ds_read_b128 v[172:175], v26 offset:9216
	ds_read_b128 v[176:179], v26 offset:13824
	ds_read_b128 v[160:163], v25
	ds_read_b128 v[180:183], v25 offset:4608
	s_waitcnt lgkmcnt(1)
	v_mfma_f32_32x32x16_bf16 a[96:111], v[160:163], v[164:167], a[96:111]
	v_mfma_f32_32x32x16_bf16 a[0:15], v[160:163], v[168:171], a[0:15]
	v_mfma_f32_32x32x16_bf16 a[16:31], v[160:163], v[172:175], a[16:31]
	v_mfma_f32_32x32x16_bf16 a[32:47], v[160:163], v[176:179], a[32:47]
	ds_read_b128 v[160:163], v25 offset:9216
	ds_read_b128 v[184:187], v26 offset:32
	ds_read_b128 v[188:191], v26 offset:4640
	v_lshl_add_u64 v[28:29], v[2:3], 0, s[34:35]
	v_lshl_add_u64 v[30:31], v[4:5], 0, s[34:35]
	s_add_i32 s2, s100, s28
	s_lshl_b32 s44, s100, 6
	global_load_dwordx4 v[32:35], v[28:29], off
	global_load_dwordx4 v[36:39], v[30:31], off
	v_lshl_add_u64 v[28:29], v[28:29], 0, s[8:9]
	v_lshl_add_u64 v[30:31], v[30:31], 0, s[8:9]
	s_lshl_b32 s2, s2, 7
	s_mov_b32 s3, s35
	global_load_dwordx4 v[40:43], v[28:29], off
	global_load_dwordx4 v[44:47], v[30:31], off
	s_waitcnt lgkmcnt(3)
	v_mfma_f32_32x32x16_bf16 a[80:95], v[180:183], v[164:167], a[80:95]
	v_mfma_f32_32x32x16_bf16 a[48:63], v[180:183], v[168:171], a[48:63]
	v_mfma_f32_32x32x16_bf16 a[64:79], v[180:183], v[172:175], a[64:79]
	v_mfma_f32_32x32x16_bf16 a[112:127], v[180:183], v[176:179], a[112:127]
	ds_read_b128 v[180:183], v25 offset:13824
	ds_read_b128 v[192:195], v26 offset:9248
	ds_read_b128 v[196:199], v26 offset:13856
	v_lshl_add_u64 v[28:29], v[2:3], 0, s[2:3]
	v_lshl_add_u64 v[30:31], v[4:5], 0, s[2:3]
	s_add_i32 s2, s44, s38
	s_lshl_b32 s2, s2, 1
	global_load_dwordx4 v[48:51], v[28:29], off
	global_load_dwordx4 v[52:55], v[30:31], off
	v_lshl_add_u64 v[28:29], v[2:3], 0, s[2:3]
	v_lshl_add_u64 v[30:31], v[4:5], 0, s[2:3]
	s_add_i32 s34, s34, s91
	s_add_i32 s2, s44, s39
	global_load_dwordx4 v[56:59], v[28:29], off
	global_load_dwordx4 v[60:63], v[30:31], off
	s_waitcnt lgkmcnt(5)
; #define GLOAD(RA, RB, kt) { _Pragma("unroll") for (int i = 0; i < 8; ++i) { const int ia = (tail && i >= 4) ? i - 4 : i; \
;     RA[i] = *(const u32x4*)(abase + ((size_t)(32 * ia) * lda + (kt) * 64) * 2 + aoff); RB[i] = *(const u32x4*)(bbase + ((size_t)(32 * i) * K + (kt) * 64) * 2 + boff); } }
; #define LWRITE(RA, RB, buf) { char* as_ = lds + (buf) * 2 * G_TILE; char* bs_ = as_ + G_TILE; _Pragma("unroll") for (int i = 0; i < 8; ++i) { *(u32x4*)(as_ + (lrow + 32 * i) * GS_B + lch * 16) = RA[i]; *(u32x4*)(bs_ + (lrow + 32 * i) * GS_B + lch * 16) = RB[i]; } }
; template <int EPI>
; DEV void gemm_tile(CParams& p, int layer, const bf16_t* __restrict__ A, int lda, const bf16_t* __restrict__ Bt, int K, int m0, int n0, int nt, char* lds, const int swave) {
;     ...
;   GLOAD(ra0, rb0, 0); GLOAD(ra1, rb1, 1); LWRITE(ra0, rb0, 0); __syncthreads();
; #pragma unroll 1
;   for (int kt = 0; kt < nk; kt += 2) {
;     if (kt + 2 < nk) GLOAD(ra0, rb0, kt + 2);
;     COMPUTE(0, ra1, rb1, 1, true);
;     __syncthreads();
	v_mfma_f32_32x32x16_bf16 a[128:143], v[160:163], v[164:167], a[128:143]
	v_mfma_f32_32x32x16_bf16 a[144:159], v[160:163], v[168:171], a[144:159]
	v_mfma_f32_32x32x16_bf16 a[160:175], v[160:163], v[172:175], a[160:175]
	v_mfma_f32_32x32x16_bf16 a[176:191], v[160:163], v[176:179], a[176:191]
	ds_read_b128 v[160:163], v25 offset:32
	v_lshl_add_u64 v[28:29], v[2:3], 0, s[34:35]
	v_lshl_add_u64 v[30:31], v[4:5], 0, s[34:35]
	s_lshl_b32 s34, s2, 1
	s_add_i32 s2, s44, s68
	global_load_dwordx4 v[64:67], v[28:29], off
	global_load_dwordx4 v[68:71], v[30:31], off
	v_lshl_add_u64 v[28:29], v[2:3], 0, s[34:35]
	v_lshl_add_u64 v[30:31], v[4:5], 0, s[34:35]
	s_lshl_b32 s34, s2, 1
	s_add_i32 s44, s44, s40
	global_load_dwordx4 v[72:75], v[28:29], off
	global_load_dwordx4 v[76:79], v[30:31], off
	s_waitcnt lgkmcnt(3)
	v_mfma_f32_32x32x16_bf16 a[192:207], v[180:183], v[164:167], a[192:207]
	v_mfma_f32_32x32x16_bf16 a[208:223], v[180:183], v[168:171], a[208:223]
	v_mfma_f32_32x32x16_bf16 a[224:239], v[180:183], v[172:175], a[224:239]
	v_mfma_f32_32x32x16_bf16 a[240:255], v[180:183], v[176:179], a[240:255]
	ds_read_b128 v[180:183], v25 offset:4640
	v_lshl_add_u64 v[28:29], v[2:3], 0, s[34:35]
	v_lshl_add_u64 v[30:31], v[4:5], 0, s[34:35]
	s_lshl_b32 s34, s44, 1
	global_load_dwordx4 v[80:83], v[28:29], off
	global_load_dwordx4 v[92:95], v[30:31], off
	v_lshl_add_u64 v[28:29], v[2:3], 0, s[34:35]
	v_lshl_add_u64 v[30:31], v[4:5], 0, s[34:35]
	global_load_dwordx4 v[100:103], v[28:29], off
	global_load_dwordx4 v[108:111], v[30:31], off
	s_waitcnt vmcnt(31)
	ds_write_b128 v8, v[84:87]
	s_waitcnt vmcnt(30)
	ds_write_b128 v9, v[88:91]
	s_waitcnt vmcnt(29)
	ds_write_b128 v18, v[96:99]
	s_waitcnt vmcnt(28)
	ds_write_b128 v19, v[104:107]
	s_waitcnt lgkmcnt(5)
	v_mfma_f32_32x32x16_bf16 a[96:111], v[160:163], v[184:187], a[96:111]
	v_mfma_f32_32x32x16_bf16 a[0:15], v[160:163], v[188:191], a[0:15]
	v_mfma_f32_32x32x16_bf16 a[16:31], v[160:163], v[192:195], a[16:31]
	v_mfma_f32_32x32x16_bf16 a[32:47], v[160:163], v[196:199], a[32:47]
	ds_read_b128 v[160:163], v25 offset:9248
	ds_read_b128 v[164:167], v26 offset:64
	ds_read_b128 v[168:171], v26 offset:4672
	s_waitcnt lgkmcnt(7)
	v_mfma_f32_32x32x16_bf16 a[80:95], v[180:183], v[184:187], a[80:95]
	v_mfma_f32_32x32x16_bf16 a[48:63], v[180:183], v[188:191], a[48:63]
	v_mfma_f32_32x32x16_bf16 a[64:79], v[180:183], v[192:195], a[64:79]
	v_mfma_f32_32x32x16_bf16 a[112:127], v[180:183], v[196:199], a[112:127]
	ds_read_b128 v[180:183], v25 offset:13856
	ds_read_b128 v[172:175], v26 offset:9280
	ds_read_b128 v[176:179], v26 offset:13888
	s_waitcnt lgkmcnt(5)
	v_mfma_f32_32x32x16_bf16 a[128:143], v[160:163], v[184:187], a[128:143]
	v_mfma_f32_32x32x16_bf16 a[144:159], v[160:163], v[188:191], a[144:159]
	v_mfma_f32_32x32x16_bf16 a[160:175], v[160:163], v[192:195], a[160:175]
	v_mfma_f32_32x32x16_bf16 a[176:191], v[160:163], v[196:199], a[176:191]
	ds_read_b128 v[160:163], v25 offset:64
	s_waitcnt lgkmcnt(3)
	v_mfma_f32_32x32x16_bf16 a[192:207], v[180:183], v[184:187], a[192:207]
	v_mfma_f32_32x32x16_bf16 a[208:223], v[180:183], v[188:191], a[208:223]
	v_mfma_f32_32x32x16_bf16 a[224:239], v[180:183], v[192:195], a[224:239]
	v_mfma_f32_32x32x16_bf16 a[240:255], v[180:183], v[196:199], a[240:255]
	ds_read_b128 v[180:183], v25 offset:4672
	s_waitcnt vmcnt(27)
	ds_write_b128 v14, v[112:115]
	s_waitcnt vmcnt(26)
	ds_write_b128 v15, v[116:119]
	s_waitcnt vmcnt(25)
	ds_write_b128 v16, v[120:123]
	s_waitcnt vmcnt(24)
	ds_write_b128 v17, v[124:127]
	s_waitcnt lgkmcnt(5)
	v_mfma_f32_32x32x16_bf16 a[96:111], v[160:163], v[164:167], a[96:111]
	v_mfma_f32_32x32x16_bf16 a[0:15], v[160:163], v[168:171], a[0:15]
	v_mfma_f32_32x32x16_bf16 a[16:31], v[160:163], v[172:175], a[16:31]
	v_mfma_f32_32x32x16_bf16 a[32:47], v[160:163], v[176:179], a[32:47]
	ds_read_b128 v[160:163], v25 offset:9280
	ds_read_b128 v[184:187], v26 offset:96
	ds_read_b128 v[188:191], v26 offset:4704
	s_waitcnt lgkmcnt(7)
	v_mfma_f32_32x32x16_bf16 a[80:95], v[180:183], v[164:167], a[80:95]
	v_mfma_f32_32x32x16_bf16 a[48:63], v[180:183], v[168:171], a[48:63]
	v_mfma_f32_32x32x16_bf16 a[64:79], v[180:183], v[172:175], a[64:79]
	v_mfma_f32_32x32x16_bf16 a[112:127], v[180:183], v[176:179], a[112:127]
	ds_read_b128 v[180:183], v25 offset:13888
	ds_read_b128 v[192:195], v26 offset:9312
	ds_read_b128 v[196:199], v26 offset:13920
	s_waitcnt lgkmcnt(5)
	v_mfma_f32_32x32x16_bf16 a[128:143], v[160:163], v[164:167], a[128:143]
	v_mfma_f32_32x32x16_bf16 a[144:159], v[160:163], v[168:171], a[144:159]
	v_mfma_f32_32x32x16_bf16 a[160:175], v[160:163], v[172:175], a[160:175]
	v_mfma_f32_32x32x16_bf16 a[176:191], v[160:163], v[176:179], a[176:191]
	ds_read_b128 v[160:163], v25 offset:96
	s_waitcnt lgkmcnt(3)
	v_mfma_f32_32x32x16_bf16 a[192:207], v[180:183], v[164:167], a[192:207]
	v_mfma_f32_32x32x16_bf16 a[208:223], v[180:183], v[168:171], a[208:223]
	v_mfma_f32_32x32x16_bf16 a[224:239], v[180:183], v[172:175], a[224:239]
	v_mfma_f32_32x32x16_bf16 a[240:255], v[180:183], v[176:179], a[240:255]
	ds_read_b128 v[180:183], v25 offset:4704
	s_waitcnt vmcnt(23)
	ds_write_b128 v10, v[128:131]
	s_waitcnt vmcnt(22)
	ds_write_b128 v11, v[132:135]
	s_waitcnt vmcnt(21)
	ds_write_b128 v12, v[136:139]
	s_waitcnt vmcnt(20)
	ds_write_b128 v13, v[140:143]
	s_waitcnt lgkmcnt(5)
	v_mfma_f32_32x32x16_bf16 a[96:111], v[160:163], v[184:187], a[96:111]
	v_mfma_f32_32x32x16_bf16 a[0:15], v[160:163], v[188:191], a[0:15]
	v_mfma_f32_32x32x16_bf16 a[16:31], v[160:163], v[192:195], a[16:31]
	v_mfma_f32_32x32x16_bf16 a[32:47], v[160:163], v[196:199], a[32:47]
	ds_read_b128 v[160:163], v25 offset:9312
	s_waitcnt lgkmcnt(5)
	v_mfma_f32_32x32x16_bf16 a[80:95], v[180:183], v[184:187], a[80:95]
	v_mfma_f32_32x32x16_bf16 a[48:63], v[180:183], v[188:191], a[48:63]
	v_mfma_f32_32x32x16_bf16 a[64:79], v[180:183], v[192:195], a[64:79]
	v_mfma_f32_32x32x16_bf16 a[112:127], v[180:183], v[196:199], a[112:127]
	ds_read_b128 v[180:183], v25 offset:13920
	s_waitcnt lgkmcnt(1)
	v_mfma_f32_32x32x16_bf16 a[128:143], v[160:163], v[184:187], a[128:143]
	v_mfma_f32_32x32x16_bf16 a[144:159], v[160:163], v[188:191], a[144:159]
	v_mfma_f32_32x32x16_bf16 a[160:175], v[160:163], v[192:195], a[160:175]
	v_mfma_f32_32x32x16_bf16 a[176:191], v[160:163], v[196:199], a[176:191]
	s_waitcnt lgkmcnt(0)
	v_mfma_f32_32x32x16_bf16 a[192:207], v[180:183], v[184:187], a[192:207]
	v_mfma_f32_32x32x16_bf16 a[208:223], v[180:183], v[188:191], a[208:223]
	v_mfma_f32_32x32x16_bf16 a[224:239], v[180:183], v[192:195], a[224:239]
	v_mfma_f32_32x32x16_bf16 a[240:255], v[180:183], v[196:199], a[240:255]
	s_waitcnt vmcnt(19)
	ds_write_b128 v20, v[144:147]
	s_waitcnt vmcnt(18)
	ds_write_b128 v21, v[148:151]
	s_waitcnt vmcnt(17)
	ds_write_b128 v22, v[152:155]
	s_waitcnt vmcnt(16)
	ds_write_b128 v23, v[156:159]

; #define GLOAD(RA, RB, kt) { _Pragma("unroll") for (int i = 0; i < 8; ++i) { const int ia = (tail && i >= 4) ? i - 4 : i; \
;     RA[i] = *(const u32x4*)(abase + ((size_t)(32 * ia) * lda + (kt) * 64) * 2 + aoff); RB[i] = *(const u32x4*)(bbase + ((size_t)(32 * i) * K + (kt) * 64) * 2 + boff); } }
; template <int EPI>
; DEV void gemm_tile(CParams& p, int layer, const bf16_t* __restrict__ A, int lda, const bf16_t* __restrict__ Bt, int K, int m0, int n0, int nt, char* lds, const int swave) {
;     ...
;     const bool more = kt + 2 < nk;
;     if (kt + 3 < nk) GLOAD(ra1, rb1, kt + 3);
;     COMPUTE(1, ra0, rb0, 0, more);
;     __syncthreads();
.LBB0_179:
	v_add_u32_e32 v200, 0x1b000, v6
	v_add_u32_e32 v201, 0x12000, v26
	s_andn2_b64 vcc, exec, s[60:61]
	s_cbranch_vccnz .Lpg_i2_nomore
	ds_read_b128 v[164:167], v201
	ds_read_b128 v[168:171], v201 offset:4608
	ds_read_b128 v[172:175], v201 offset:9216
	ds_read_b128 v[176:179], v201 offset:13824
	ds_read_b128 v[160:163], v200
	ds_read_b128 v[180:183], v200 offset:4608
	s_waitcnt lgkmcnt(1)
	v_mfma_f32_32x32x16_bf16 a[96:111], v[160:163], v[164:167], a[96:111]
	v_mfma_f32_32x32x16_bf16 a[0:15], v[160:163], v[168:171], a[0:15]
	v_mfma_f32_32x32x16_bf16 a[16:31], v[160:163], v[172:175], a[16:31]
	v_mfma_f32_32x32x16_bf16 a[32:47], v[160:163], v[176:179], a[32:47]
	ds_read_b128 v[160:163], v200 offset:9216
	ds_read_b128 v[184:187], v201 offset:32
	ds_read_b128 v[188:191], v201 offset:4640
	s_lshl_b32 s34, s2, 7
	s_lshl_b32 s44, s2, 6
	v_lshl_add_u64 v[28:29], v[2:3], 0, s[34:35]
	v_lshl_add_u64 v[30:31], v[4:5], 0, s[34:35]
	s_add_i32 s2, s2, s28
	global_load_dwordx4 v[84:87], v[28:29], off
	global_load_dwordx4 v[88:91], v[30:31], off
	v_lshl_add_u64 v[28:29], v[28:29], 0, s[8:9]
	v_lshl_add_u64 v[30:31], v[30:31], 0, s[8:9]
	s_lshl_b32 s2, s2, 7
	s_mov_b32 s3, s35
	global_load_dwordx4 v[96:99], v[28:29], off
	global_load_dwordx4 v[104:107], v[30:31], off
	s_waitcnt lgkmcnt(3)
	v_mfma_f32_32x32x16_bf16 a[80:95], v[180:183], v[164:167], a[80:95]
	v_mfma_f32_32x32x16_bf16 a[48:63], v[180:183], v[168:171], a[48:63]
	v_mfma_f32_32x32x16_bf16 a[64:79], v[180:183], v[172:175], a[64:79]
	v_mfma_f32_32x32x16_bf16 a[112:127], v[180:183], v[176:179], a[112:127]
	ds_read_b128 v[180:183], v200 offset:13824
	ds_read_b128 v[192:195], v201 offset:9248
	ds_read_b128 v[196:199], v201 offset:13856
	v_lshl_add_u64 v[28:29], v[2:3], 0, s[2:3]
	v_lshl_add_u64 v[30:31], v[4:5], 0, s[2:3]
	s_add_i32 s2, s44, s38
	s_lshl_b32 s2, s2, 1
	global_load_dwordx4 v[112:115], v[28:29], off
	global_load_dwordx4 v[116:119], v[30:31], off
	v_lshl_add_u64 v[28:29], v[2:3], 0, s[2:3]
	v_lshl_add_u64 v[30:31], v[4:5], 0, s[2:3]
	s_add_i32 s34, s34, s91
	s_add_i32 s2, s44, s39
	global_load_dwordx4 v[120:123], v[28:29], off
	global_load_dwordx4 v[124:127], v[30:31], off
	s_waitcnt lgkmcnt(5)
	v_mfma_f32_32x32x16_bf16 a[128:143], v[160:163], v[164:167], a[128:143]
	v_mfma_f32_32x32x16_bf16 a[144:159], v[160:163], v[168:171], a[144:159]
	v_mfma_f32_32x32x16_bf16 a[160:175], v[160:163], v[172:175], a[160:175]
	v_mfma_f32_32x32x16_bf16 a[176:191], v[160:163], v[176:179], a[176:191]
	ds_read_b128 v[160:163], v200 offset:32
	v_lshl_add_u64 v[28:29], v[2:3], 0, s[34:35]
	v_lshl_add_u64 v[30:31], v[4:5], 0, s[34:35]
	s_lshl_b32 s34, s2, 1
	s_add_i32 s2, s44, s68
	global_load_dwordx4 v[128:131], v[28:29], off
	global_load_dwordx4 v[132:135], v[30:31], off
	v_lshl_add_u64 v[28:29], v[2:3], 0, s[34:35]
	v_lshl_add_u64 v[30:31], v[4:5], 0, s[34:35]
	s_lshl_b32 s34, s2, 1
	s_add_i32 s44, s44, s40
	global_load_dwordx4 v[136:139], v[28:29], off
	global_load_dwordx4 v[140:143], v[30:31], off
	s_waitcnt lgkmcnt(3)
	v_mfma_f32_32x32x16_bf16 a[192:207], v[180:183], v[164:167], a[192:207]
	v_mfma_f32_32x32x16_bf16 a[208:223], v[180:183], v[168:171], a[208:223]
	v_mfma_f32_32x32x16_bf16 a[224:239], v[180:183], v[172:175], a[224:239]
	v_mfma_f32_32x32x16_bf16 a[240:255], v[180:183], v[176:179], a[240:255]
	ds_read_b128 v[180:183], v200 offset:4640
	v_lshl_add_u64 v[28:29], v[2:3], 0, s[34:35]
	v_lshl_add_u64 v[30:31], v[4:5], 0, s[34:35]
	s_lshl_b32 s34, s44, 1
	global_load_dwordx4 v[144:147], v[28:29], off
	global_load_dwordx4 v[148:151], v[30:31], off
	v_lshl_add_u64 v[28:29], v[2:3], 0, s[34:35]
	v_lshl_add_u64 v[30:31], v[4:5], 0, s[34:35]
	global_load_dwordx4 v[152:155], v[28:29], off
	global_load_dwordx4 v[156:159], v[30:31], off
	s_waitcnt vmcnt(31)
	ds_write_b128 v7, v[32:35]
	s_waitcnt vmcnt(30)
	ds_write_b128 v7, v[36:39] offset:36864
	s_waitcnt vmcnt(29)
	ds_write_b128 v7, v[40:43] offset:4608
	s_waitcnt vmcnt(28)
	ds_write_b128 v7, v[44:47] offset:41472
	s_waitcnt lgkmcnt(5)
	v_mfma_f32_32x32x16_bf16 a[96:111], v[160:163], v[184:187], a[96:111]
	v_mfma_f32_32x32x16_bf16 a[0:15], v[160:163], v[188:191], a[0:15]
	v_mfma_f32_32x32x16_bf16 a[16:31], v[160:163], v[192:195], a[16:31]
	v_mfma_f32_32x32x16_bf16 a[32:47], v[160:163], v[196:199], a[32:47]
	ds_read_b128 v[160:163], v200 offset:9248
	ds_read_b128 v[164:167], v201 offset:64
	ds_read_b128 v[168:171], v201 offset:4672
	s_waitcnt lgkmcnt(7)
; template <int EPI>
; DEV void gemm_tile(CParams& p, int layer, const bf16_t* __restrict__ A, int lda, const bf16_t* __restrict__ Bt, int K, int m0, int n0, int nt, char* lds, const int swave) {
;     ...
;     COMPUTE(1, ra0, rb0, 0, more);
;     __syncthreads();
	v_mfma_f32_32x32x16_bf16 a[80:95], v[180:183], v[184:187], a[80:95]
	v_mfma_f32_32x32x16_bf16 a[48:63], v[180:183], v[188:191], a[48:63]
	v_mfma_f32_32x32x16_bf16 a[64:79], v[180:183], v[192:195], a[64:79]
	v_mfma_f32_32x32x16_bf16 a[112:127], v[180:183], v[196:199], a[112:127]
	ds_read_b128 v[180:183], v200 offset:13856
	ds_read_b128 v[172:175], v201 offset:9280
	ds_read_b128 v[176:179], v201 offset:13888
	s_waitcnt lgkmcnt(5)
	v_mfma_f32_32x32x16_bf16 a[128:143], v[160:163], v[184:187], a[128:143]
	v_mfma_f32_32x32x16_bf16 a[144:159], v[160:163], v[188:191], a[144:159]
	v_mfma_f32_32x32x16_bf16 a[160:175], v[160:163], v[192:195], a[160:175]
	v_mfma_f32_32x32x16_bf16 a[176:191], v[160:163], v[196:199], a[176:191]
	ds_read_b128 v[160:163], v200 offset:64
	s_waitcnt lgkmcnt(3)
	v_mfma_f32_32x32x16_bf16 a[192:207], v[180:183], v[184:187], a[192:207]
	v_mfma_f32_32x32x16_bf16 a[208:223], v[180:183], v[188:191], a[208:223]
	v_mfma_f32_32x32x16_bf16 a[224:239], v[180:183], v[192:195], a[224:239]
	v_mfma_f32_32x32x16_bf16 a[240:255], v[180:183], v[196:199], a[240:255]
	ds_read_b128 v[180:183], v200 offset:4672
	s_waitcnt vmcnt(27)
	ds_write_b128 v7, v[48:51] offset:9216
	s_waitcnt vmcnt(26)
	ds_write_b128 v7, v[52:55] offset:46080
	s_waitcnt vmcnt(25)
	ds_write_b128 v7, v[56:59] offset:13824
	s_waitcnt vmcnt(24)
	ds_write_b128 v7, v[60:63] offset:50688
	s_waitcnt lgkmcnt(5)
	v_mfma_f32_32x32x16_bf16 a[96:111], v[160:163], v[164:167], a[96:111]
	v_mfma_f32_32x32x16_bf16 a[0:15], v[160:163], v[168:171], a[0:15]
	v_mfma_f32_32x32x16_bf16 a[16:31], v[160:163], v[172:175], a[16:31]
	v_mfma_f32_32x32x16_bf16 a[32:47], v[160:163], v[176:179], a[32:47]
	ds_read_b128 v[160:163], v200 offset:9280
	ds_read_b128 v[184:187], v201 offset:96
	ds_read_b128 v[188:191], v201 offset:4704
	s_waitcnt lgkmcnt(7)
	v_mfma_f32_32x32x16_bf16 a[80:95], v[180:183], v[164:167], a[80:95]
	v_mfma_f32_32x32x16_bf16 a[48:63], v[180:183], v[168:171], a[48:63]
	v_mfma_f32_32x32x16_bf16 a[64:79], v[180:183], v[172:175], a[64:79]
	v_mfma_f32_32x32x16_bf16 a[112:127], v[180:183], v[176:179], a[112:127]
	ds_read_b128 v[180:183], v200 offset:13888
	ds_read_b128 v[192:195], v201 offset:9312
	ds_read_b128 v[196:199], v201 offset:13920
	s_waitcnt lgkmcnt(5)
	v_mfma_f32_32x32x16_bf16 a[128:143], v[160:163], v[164:167], a[128:143]
	v_mfma_f32_32x32x16_bf16 a[144:159], v[160:163], v[168:171], a[144:159]
	v_mfma_f32_32x32x16_bf16 a[160:175], v[160:163], v[172:175], a[160:175]
	v_mfma_f32_32x32x16_bf16 a[176:191], v[160:163], v[176:179], a[176:191]
	ds_read_b128 v[160:163], v200 offset:96
	s_waitcnt lgkmcnt(3)
	v_mfma_f32_32x32x16_bf16 a[192:207], v[180:183], v[164:167], a[192:207]
	v_mfma_f32_32x32x16_bf16 a[208:223], v[180:183], v[168:171], a[208:223]
	v_mfma_f32_32x32x16_bf16 a[224:239], v[180:183], v[172:175], a[224:239]
	v_mfma_f32_32x32x16_bf16 a[240:255], v[180:183], v[176:179], a[240:255]
	ds_read_b128 v[180:183], v200 offset:4704
	s_waitcnt vmcnt(23)
	ds_write_b128 v7, v[64:67] offset:18432
	s_waitcnt vmcnt(22)
	ds_write_b128 v7, v[68:71] offset:55296
	s_waitcnt vmcnt(21)
	ds_write_b128 v7, v[72:75] offset:23040
	s_waitcnt vmcnt(20)
	ds_write_b128 v7, v[76:79] offset:59904
	s_waitcnt lgkmcnt(5)
	v_mfma_f32_32x32x16_bf16 a[96:111], v[160:163], v[184:187], a[96:111]
	v_mfma_f32_32x32x16_bf16 a[0:15], v[160:163], v[188:191], a[0:15]
	v_mfma_f32_32x32x16_bf16 a[16:31], v[160:163], v[192:195], a[16:31]
	v_mfma_f32_32x32x16_bf16 a[32:47], v[160:163], v[196:199], a[32:47]
	ds_read_b128 v[160:163], v200 offset:9312
	s_waitcnt lgkmcnt(5)
	v_mfma_f32_32x32x16_bf16 a[80:95], v[180:183], v[184:187], a[80:95]
	v_mfma_f32_32x32x16_bf16 a[48:63], v[180:183], v[188:191], a[48:63]
	v_mfma_f32_32x32x16_bf16 a[64:79], v[180:183], v[192:195], a[64:79]
	v_mfma_f32_32x32x16_bf16 a[112:127], v[180:183], v[196:199], a[112:127]
	ds_read_b128 v[180:183], v200 offset:13920
	s_waitcnt lgkmcnt(1)
	v_mfma_f32_32x32x16_bf16 a[128:143], v[160:163], v[184:187], a[128:143]
	v_mfma_f32_32x32x16_bf16 a[144:159], v[160:163], v[188:191], a[144:159]
	v_mfma_f32_32x32x16_bf16 a[160:175], v[160:163], v[192:195], a[160:175]
	v_mfma_f32_32x32x16_bf16 a[176:191], v[160:163], v[196:199], a[176:191]
	s_waitcnt lgkmcnt(0)
	v_mfma_f32_32x32x16_bf16 a[192:207], v[180:183], v[184:187], a[192:207]
	v_mfma_f32_32x32x16_bf16 a[208:223], v[180:183], v[188:191], a[208:223]
	v_mfma_f32_32x32x16_bf16 a[224:239], v[180:183], v[192:195], a[224:239]
	v_mfma_f32_32x32x16_bf16 a[240:255], v[180:183], v[196:199], a[240:255]
	s_waitcnt vmcnt(19)
	ds_write_b128 v7, v[80:83] offset:27648
	s_waitcnt vmcnt(18)
	ds_write_b128 v7, v[92:95] offset:64512
	s_waitcnt vmcnt(17)
	ds_write_b128 v7, v[100:103] offset:32256
	s_waitcnt vmcnt(16)
	ds_write_b128 v24, v[108:111]
	s_branch .LBB0_158

; #define GLOAD(RA, RB, kt) { _Pragma("unroll") for (int i = 0; i < 8; ++i) { const int ia = (tail && i >= 4) ? i - 4 : i; \
;     RA[i] = *(const u32x4*)(abase + ((size_t)(32 * ia) * lda + (kt) * 64) * 2 + aoff); RB[i] = *(const u32x4*)(bbase + ((size_t)(32 * i) * K + (kt) * 64) * 2 + boff); } }
; #define LWRITE(RA, RB, buf) { char* as_ = lds + (buf) * 2 * G_TILE; char* bs_ = as_ + G_TILE; _Pragma("unroll") for (int i = 0; i < 8; ++i) { *(u32x4*)(as_ + (lrow + 32 * i) * GS_B + lch * 16) = RA[i]; *(u32x4*)(bs_ + (lrow + 32 * i) * GS_B + lch * 16) = RB[i]; } }
; template <int EPI>
; DEV void gemm_tile(CParams& p, int layer, const bf16_t* __restrict__ A, int lda, const bf16_t* __restrict__ Bt, int K, int m0, int n0, int nt, char* lds, const int swave) {
;     ...
;   const char* asr = lds + (wm * 128 + lr) * GS_B + hh * 16;
;   const char* bsr = lds + G_TILE + (wn * 128 + lr) * GS_B + hh * 16;
;   char* wsw = lds + lrow * GS_B + lch * 16;
;     ...
;   GLOAD(ra0, rb0, 0); GLOAD(ra1, rb1, 1); LWRITE(ra0, rb0, 0); __syncthreads();
; #pragma unroll 1
;   for (int kt = 0; kt < nk; kt += 2) {
;     if (kt + 2 < nk) GLOAD(ra0, rb0, kt + 2);
;     COMPUTE(0, ra1, rb1, 1, true);
;     __syncthreads();
.LBB0_921:
	s_cmp_eq_u32 s42, 0
	s_cbranch_scc0 .Lzi_i3
	ds_read_b128 v[184:187], v45
	ds_read_b128 v[188:191], v45 offset:4608
	ds_read_b128 v[192:195], v45 offset:9216
	ds_read_b128 v[196:199], v45 offset:13824
	ds_read_b128 v[180:183], v49
	ds_read_b128 v[204:207], v49 offset:4608
	s_waitcnt lgkmcnt(1)
	v_mfma_f32_32x32x16_bf16 a[0:15], v[180:183], v[184:187], 0
	v_mfma_f32_32x32x16_bf16 a[16:31], v[180:183], v[188:191], 0
	v_mfma_f32_32x32x16_bf16 a[32:47], v[180:183], v[192:195], 0
	v_mfma_f32_32x32x16_bf16 a[48:63], v[180:183], v[196:199], 0
	ds_read_b128 v[180:183], v49 offset:9216
	ds_read_b128 v[208:211], v45 offset:32
	ds_read_b128 v[212:215], v45 offset:4640
	v_lshl_add_u64 v[50:51], v[0:1], 0, s[34:35]
	global_load_dwordx4 v[52:55], v[50:51], off
	v_lshl_add_u64 v[50:51], v[2:3], 0, s[34:35]
	s_or_b32 s2, s34, 0x10000
	s_mov_b32 s3, s35
	global_load_dwordx4 v[56:59], v[50:51], off
	v_lshl_add_u64 v[50:51], v[0:1], 0, s[2:3]
	global_load_dwordx4 v[60:63], v[50:51], off
	v_lshl_add_u64 v[50:51], v[2:3], 0, s[2:3]
	s_or_b32 s2, s34, 0x20000
	global_load_dwordx4 v[64:67], v[50:51], off
	s_waitcnt lgkmcnt(3)
	v_mfma_f32_32x32x16_bf16 a[64:79], v[204:207], v[184:187], 0
	v_mfma_f32_32x32x16_bf16 a[80:95], v[204:207], v[188:191], 0
	v_mfma_f32_32x32x16_bf16 a[96:111], v[204:207], v[192:195], 0
	v_mfma_f32_32x32x16_bf16 a[112:127], v[204:207], v[196:199], 0
	ds_read_b128 v[204:207], v49 offset:13824
	ds_read_b128 v[216:219], v45 offset:9248
	ds_read_b128 v[220:223], v45 offset:13856
	v_lshl_add_u64 v[50:51], v[0:1], 0, s[2:3]
	global_load_dwordx4 v[68:71], v[50:51], off
	v_lshl_add_u64 v[50:51], v[2:3], 0, s[2:3]
	s_or_b32 s2, s34, 0x30000
	global_load_dwordx4 v[72:75], v[50:51], off
	v_lshl_add_u64 v[50:51], v[0:1], 0, s[2:3]
	global_load_dwordx4 v[76:79], v[50:51], off
	v_lshl_add_u64 v[50:51], v[2:3], 0, s[2:3]
	s_or_b32 s2, s34, 0x40000
	global_load_dwordx4 v[80:83], v[50:51], off
	s_waitcnt lgkmcnt(5)
	v_mfma_f32_32x32x16_bf16 a[128:143], v[180:183], v[184:187], 0
	v_mfma_f32_32x32x16_bf16 a[144:159], v[180:183], v[188:191], 0
	v_mfma_f32_32x32x16_bf16 a[160:175], v[180:183], v[192:195], 0
	v_mfma_f32_32x32x16_bf16 a[176:191], v[180:183], v[196:199], 0
	ds_read_b128 v[180:183], v49 offset:32
	v_lshl_add_u64 v[50:51], v[0:1], 0, s[2:3]
	global_load_dwordx4 v[84:87], v[50:51], off
	v_lshl_add_u64 v[50:51], v[2:3], 0, s[2:3]
	s_or_b32 s2, s34, 0x50000
	global_load_dwordx4 v[88:91], v[50:51], off
	v_lshl_add_u64 v[50:51], v[0:1], 0, s[2:3]
	global_load_dwordx4 v[92:95], v[50:51], off
	v_lshl_add_u64 v[50:51], v[2:3], 0, s[2:3]
	s_or_b32 s2, s34, 0x60000
	global_load_dwordx4 v[112:115], v[50:51], off
	s_waitcnt lgkmcnt(3)
	v_mfma_f32_32x32x16_bf16 a[192:207], v[204:207], v[184:187], 0
	v_mfma_f32_32x32x16_bf16 a[208:223], v[204:207], v[188:191], 0
	v_mfma_f32_32x32x16_bf16 a[224:239], v[204:207], v[192:195], 0
	v_mfma_f32_32x32x16_bf16 a[240:255], v[204:207], v[196:199], 0
	ds_read_b128 v[204:207], v49 offset:4640
	v_lshl_add_u64 v[50:51], v[0:1], 0, s[2:3]
	global_load_dwordx4 v[124:127], v[50:51], off
	v_lshl_add_u64 v[50:51], v[2:3], 0, s[2:3]
	s_or_b32 s34, s34, 0x70000
	global_load_dwordx4 v[140:143], v[50:51], off
	v_lshl_add_u64 v[50:51], v[0:1], 0, s[34:35]
	global_load_dwordx4 v[152:155], v[50:51], off
	v_lshl_add_u64 v[50:51], v[2:3], 0, s[34:35]
	global_load_dwordx4 v[172:175], v[50:51], off
	s_waitcnt vmcnt(31)
	ds_write_b128 v31, v[104:107]
	s_waitcnt vmcnt(30)
	ds_write_b128 v32, v[108:111]
	s_waitcnt vmcnt(29)
	ds_write_b128 v41, v[96:99]
	s_waitcnt vmcnt(28)
	ds_write_b128 v42, v[100:103]
	s_waitcnt lgkmcnt(5)
	v_mfma_f32_32x32x16_bf16 a[0:15], v[180:183], v[208:211], a[0:15]
	v_mfma_f32_32x32x16_bf16 a[16:31], v[180:183], v[212:215], a[16:31]
	v_mfma_f32_32x32x16_bf16 a[32:47], v[180:183], v[216:219], a[32:47]
	v_mfma_f32_32x32x16_bf16 a[48:63], v[180:183], v[220:223], a[48:63]
	ds_read_b128 v[180:183], v49 offset:9248
	ds_read_b128 v[184:187], v45 offset:64
	ds_read_b128 v[188:191], v45 offset:4672
	s_waitcnt lgkmcnt(7)
	v_mfma_f32_32x32x16_bf16 a[64:79], v[204:207], v[208:211], a[64:79]
	v_mfma_f32_32x32x16_bf16 a[80:95], v[204:207], v[212:215], a[80:95]
	v_mfma_f32_32x32x16_bf16 a[96:111], v[204:207], v[216:219], a[96:111]
	v_mfma_f32_32x32x16_bf16 a[112:127], v[204:207], v[220:223], a[112:127]
	ds_read_b128 v[204:207], v49 offset:13856
	ds_read_b128 v[192:195], v45 offset:9280
	ds_read_b128 v[196:199], v45 offset:13888
	s_waitcnt lgkmcnt(5)
	v_mfma_f32_32x32x16_bf16 a[128:143], v[180:183], v[208:211], a[128:143]
	v_mfma_f32_32x32x16_bf16 a[144:159], v[180:183], v[212:215], a[144:159]
	v_mfma_f32_32x32x16_bf16 a[160:175], v[180:183], v[216:219], a[160:175]
	v_mfma_f32_32x32x16_bf16 a[176:191], v[180:183], v[220:223], a[176:191]
	ds_read_b128 v[180:183], v49 offset:64
	s_waitcnt lgkmcnt(3)
	v_mfma_f32_32x32x16_bf16 a[192:207], v[204:207], v[208:211], a[192:207]
	v_mfma_f32_32x32x16_bf16 a[208:223], v[204:207], v[212:215], a[208:223]
	v_mfma_f32_32x32x16_bf16 a[224:239], v[204:207], v[216:219], a[224:239]
	v_mfma_f32_32x32x16_bf16 a[240:255], v[204:207], v[220:223], a[240:255]
	ds_read_b128 v[204:207], v49 offset:4672
	s_waitcnt vmcnt(27)
	ds_write_b128 v37, v[116:119]
	s_waitcnt vmcnt(26)
	ds_write_b128 v38, v[120:123]
	s_waitcnt vmcnt(25)
	ds_write_b128 v39, v[128:131]
	s_waitcnt vmcnt(24)
	ds_write_b128 v40, v[132:135]
	s_waitcnt lgkmcnt(5)
	v_mfma_f32_32x32x16_bf16 a[0:15], v[180:183], v[184:187], a[0:15]
	v_mfma_f32_32x32x16_bf16 a[16:31], v[180:183], v[188:191], a[16:31]
	v_mfma_f32_32x32x16_bf16 a[32:47], v[180:183], v[192:195], a[32:47]
	v_mfma_f32_32x32x16_bf16 a[48:63], v[180:183], v[196:199], a[48:63]
	ds_read_b128 v[180:183], v49 offset:9280
	ds_read_b128 v[208:211], v45 offset:96
	ds_read_b128 v[212:215], v45 offset:4704
	s_waitcnt lgkmcnt(7)
; #define GLOAD(RA, RB, kt) { _Pragma("unroll") for (int i = 0; i < 8; ++i) { const int ia = (tail && i >= 4) ? i - 4 : i; \
;     RA[i] = *(const u32x4*)(abase + ((size_t)(32 * ia) * lda + (kt) * 64) * 2 + aoff); RB[i] = *(const u32x4*)(bbase + ((size_t)(32 * i) * K + (kt) * 64) * 2 + boff); } }
; #define LWRITE(RA, RB, buf) { char* as_ = lds + (buf) * 2 * G_TILE; char* bs_ = as_ + G_TILE; _Pragma("unroll") for (int i = 0; i < 8; ++i) { *(u32x4*)(as_ + (lrow + 32 * i) * GS_B + lch * 16) = RA[i]; *(u32x4*)(bs_ + (lrow + 32 * i) * GS_B + lch * 16) = RB[i]; } }
; template <int EPI>
; DEV void gemm_tile(CParams& p, int layer, const bf16_t* __restrict__ A, int lda, const bf16_t* __restrict__ Bt, int K, int m0, int n0, int nt, char* lds, const int swave) {
;     ...
;   GLOAD(ra0, rb0, 0); GLOAD(ra1, rb1, 1); LWRITE(ra0, rb0, 0); __syncthreads();
; #pragma unroll 1
;   for (int kt = 0; kt < nk; kt += 2) {
;     if (kt + 2 < nk) GLOAD(ra0, rb0, kt + 2);
;     COMPUTE(0, ra1, rb1, 1, true);
;     __syncthreads();
	v_mfma_f32_32x32x16_bf16 a[64:79], v[204:207], v[184:187], a[64:79]
	v_mfma_f32_32x32x16_bf16 a[80:95], v[204:207], v[188:191], a[80:95]
	v_mfma_f32_32x32x16_bf16 a[96:111], v[204:207], v[192:195], a[96:111]
	v_mfma_f32_32x32x16_bf16 a[112:127], v[204:207], v[196:199], a[112:127]
	ds_read_b128 v[204:207], v49 offset:13888
	ds_read_b128 v[216:219], v45 offset:9312
	ds_read_b128 v[220:223], v45 offset:13920
	s_waitcnt lgkmcnt(5)
	v_mfma_f32_32x32x16_bf16 a[128:143], v[180:183], v[184:187], a[128:143]
	v_mfma_f32_32x32x16_bf16 a[144:159], v[180:183], v[188:191], a[144:159]
	v_mfma_f32_32x32x16_bf16 a[160:175], v[180:183], v[192:195], a[160:175]
	v_mfma_f32_32x32x16_bf16 a[176:191], v[180:183], v[196:199], a[176:191]
	ds_read_b128 v[180:183], v49 offset:96
	s_waitcnt lgkmcnt(3)
	v_mfma_f32_32x32x16_bf16 a[192:207], v[204:207], v[184:187], a[192:207]
	v_mfma_f32_32x32x16_bf16 a[208:223], v[204:207], v[188:191], a[208:223]
	v_mfma_f32_32x32x16_bf16 a[224:239], v[204:207], v[192:195], a[224:239]
	v_mfma_f32_32x32x16_bf16 a[240:255], v[204:207], v[196:199], a[240:255]
	ds_read_b128 v[204:207], v49 offset:4704
	s_waitcnt vmcnt(23)
	ds_write_b128 v33, v[136:139]
	s_waitcnt vmcnt(22)
	ds_write_b128 v34, v[144:147]
	s_waitcnt vmcnt(21)
	ds_write_b128 v35, v[148:151]
	s_waitcnt vmcnt(20)
	ds_write_b128 v36, v[156:159]
	s_waitcnt lgkmcnt(5)
	v_mfma_f32_32x32x16_bf16 a[0:15], v[180:183], v[208:211], a[0:15]
	v_mfma_f32_32x32x16_bf16 a[16:31], v[180:183], v[212:215], a[16:31]
	v_mfma_f32_32x32x16_bf16 a[32:47], v[180:183], v[216:219], a[32:47]
	v_mfma_f32_32x32x16_bf16 a[48:63], v[180:183], v[220:223], a[48:63]
	ds_read_b128 v[180:183], v49 offset:9312
	s_waitcnt lgkmcnt(5)
	v_mfma_f32_32x32x16_bf16 a[64:79], v[204:207], v[208:211], a[64:79]
	v_mfma_f32_32x32x16_bf16 a[80:95], v[204:207], v[212:215], a[80:95]
	v_mfma_f32_32x32x16_bf16 a[96:111], v[204:207], v[216:219], a[96:111]
	v_mfma_f32_32x32x16_bf16 a[112:127], v[204:207], v[220:223], a[112:127]
	ds_read_b128 v[204:207], v49 offset:13920
	s_waitcnt lgkmcnt(1)
	v_mfma_f32_32x32x16_bf16 a[128:143], v[180:183], v[208:211], a[128:143]
	v_mfma_f32_32x32x16_bf16 a[144:159], v[180:183], v[212:215], a[144:159]
	v_mfma_f32_32x32x16_bf16 a[160:175], v[180:183], v[216:219], a[160:175]
	v_mfma_f32_32x32x16_bf16 a[176:191], v[180:183], v[220:223], a[176:191]
	s_waitcnt lgkmcnt(0)
	v_mfma_f32_32x32x16_bf16 a[192:207], v[204:207], v[208:211], a[192:207]
	v_mfma_f32_32x32x16_bf16 a[208:223], v[204:207], v[212:215], a[208:223]
	v_mfma_f32_32x32x16_bf16 a[224:239], v[204:207], v[216:219], a[224:239]
	v_mfma_f32_32x32x16_bf16 a[240:255], v[204:207], v[220:223], a[240:255]
	s_waitcnt vmcnt(19)
	ds_write_b128 v43, v[160:163]
	s_waitcnt vmcnt(18)
	ds_write_b128 v44, v[164:167]
	s_waitcnt vmcnt(17)
	ds_write_b128 v46, v[168:171]
	s_waitcnt vmcnt(16)
	ds_write_b128 v47, v[176:179]
	s_branch .LBB0_937
.Lzi_i3:
	ds_read_b128 v[184:187], v45
	ds_read_b128 v[188:191], v45 offset:4608
	ds_read_b128 v[192:195], v45 offset:9216
	ds_read_b128 v[196:199], v45 offset:13824
	ds_read_b128 v[180:183], v49
	ds_read_b128 v[204:207], v49 offset:4608
	s_waitcnt lgkmcnt(1)
	v_mfma_f32_32x32x16_bf16 a[0:15], v[180:183], v[184:187], a[0:15]
	v_mfma_f32_32x32x16_bf16 a[16:31], v[180:183], v[188:191], a[16:31]
	v_mfma_f32_32x32x16_bf16 a[32:47], v[180:183], v[192:195], a[32:47]
	v_mfma_f32_32x32x16_bf16 a[48:63], v[180:183], v[196:199], a[48:63]
	ds_read_b128 v[180:183], v49 offset:9216
	ds_read_b128 v[208:211], v45 offset:32
	ds_read_b128 v[212:215], v45 offset:4640
	v_lshl_add_u64 v[50:51], v[0:1], 0, s[34:35]
	global_load_dwordx4 v[52:55], v[50:51], off
	v_lshl_add_u64 v[50:51], v[2:3], 0, s[34:35]
	s_or_b32 s2, s34, 0x10000
	s_mov_b32 s3, s35
	global_load_dwordx4 v[56:59], v[50:51], off
	v_lshl_add_u64 v[50:51], v[0:1], 0, s[2:3]
	global_load_dwordx4 v[60:63], v[50:51], off
	v_lshl_add_u64 v[50:51], v[2:3], 0, s[2:3]
	s_or_b32 s2, s34, 0x20000
	global_load_dwordx4 v[64:67], v[50:51], off
	s_waitcnt lgkmcnt(3)
	v_mfma_f32_32x32x16_bf16 a[64:79], v[204:207], v[184:187], a[64:79]
	v_mfma_f32_32x32x16_bf16 a[80:95], v[204:207], v[188:191], a[80:95]
	v_mfma_f32_32x32x16_bf16 a[96:111], v[204:207], v[192:195], a[96:111]
	v_mfma_f32_32x32x16_bf16 a[112:127], v[204:207], v[196:199], a[112:127]
	ds_read_b128 v[204:207], v49 offset:13824
	ds_read_b128 v[216:219], v45 offset:9248
	ds_read_b128 v[220:223], v45 offset:13856
	v_lshl_add_u64 v[50:51], v[0:1], 0, s[2:3]
	global_load_dwordx4 v[68:71], v[50:51], off
	v_lshl_add_u64 v[50:51], v[2:3], 0, s[2:3]
	s_or_b32 s2, s34, 0x30000
	global_load_dwordx4 v[72:75], v[50:51], off
	v_lshl_add_u64 v[50:51], v[0:1], 0, s[2:3]
	global_load_dwordx4 v[76:79], v[50:51], off
	v_lshl_add_u64 v[50:51], v[2:3], 0, s[2:3]
	s_or_b32 s2, s34, 0x40000
	global_load_dwordx4 v[80:83], v[50:51], off
	s_waitcnt lgkmcnt(5)
	v_mfma_f32_32x32x16_bf16 a[128:143], v[180:183], v[184:187], a[128:143]
	v_mfma_f32_32x32x16_bf16 a[144:159], v[180:183], v[188:191], a[144:159]
	v_mfma_f32_32x32x16_bf16 a[160:175], v[180:183], v[192:195], a[160:175]
	v_mfma_f32_32x32x16_bf16 a[176:191], v[180:183], v[196:199], a[176:191]
	ds_read_b128 v[180:183], v49 offset:32
	v_lshl_add_u64 v[50:51], v[0:1], 0, s[2:3]
	global_load_dwordx4 v[84:87], v[50:51], off
	v_lshl_add_u64 v[50:51], v[2:3], 0, s[2:3]
	s_or_b32 s2, s34, 0x50000
	global_load_dwordx4 v[88:91], v[50:51], off
	v_lshl_add_u64 v[50:51], v[0:1], 0, s[2:3]
	global_load_dwordx4 v[92:95], v[50:51], off
	v_lshl_add_u64 v[50:51], v[2:3], 0, s[2:3]
	s_or_b32 s2, s34, 0x60000
	global_load_dwordx4 v[112:115], v[50:51], off
	s_waitcnt lgkmcnt(3)
; #define GLOAD(RA, RB, kt) { _Pragma("unroll") for (int i = 0; i < 8; ++i) { const int ia = (tail && i >= 4) ? i - 4 : i; \
;     RA[i] = *(const u32x4*)(abase + ((size_t)(32 * ia) * lda + (kt) * 64) * 2 + aoff); RB[i] = *(const u32x4*)(bbase + ((size_t)(32 * i) * K + (kt) * 64) * 2 + boff); } }
; #define LWRITE(RA, RB, buf) { char* as_ = lds + (buf) * 2 * G_TILE; char* bs_ = as_ + G_TILE; _Pragma("unroll") for (int i = 0; i < 8; ++i) { *(u32x4*)(as_ + (lrow + 32 * i) * GS_B + lch * 16) = RA[i]; *(u32x4*)(bs_ + (lrow + 32 * i) * GS_B + lch * 16) = RB[i]; } }
; template <int EPI>
; DEV void gemm_tile(CParams& p, int layer, const bf16_t* __restrict__ A, int lda, const bf16_t* __restrict__ Bt, int K, int m0, int n0, int nt, char* lds, const int swave) {
;     ...
;   GLOAD(ra0, rb0, 0); GLOAD(ra1, rb1, 1); LWRITE(ra0, rb0, 0); __syncthreads();
; #pragma unroll 1
;   for (int kt = 0; kt < nk; kt += 2) {
;     if (kt + 2 < nk) GLOAD(ra0, rb0, kt + 2);
;     COMPUTE(0, ra1, rb1, 1, true);
;     __syncthreads();
	v_mfma_f32_32x32x16_bf16 a[192:207], v[204:207], v[184:187], a[192:207]
	v_mfma_f32_32x32x16_bf16 a[208:223], v[204:207], v[188:191], a[208:223]
	v_mfma_f32_32x32x16_bf16 a[224:239], v[204:207], v[192:195], a[224:239]
	v_mfma_f32_32x32x16_bf16 a[240:255], v[204:207], v[196:199], a[240:255]
	ds_read_b128 v[204:207], v49 offset:4640
	v_lshl_add_u64 v[50:51], v[0:1], 0, s[2:3]
	global_load_dwordx4 v[124:127], v[50:51], off
	v_lshl_add_u64 v[50:51], v[2:3], 0, s[2:3]
	s_or_b32 s34, s34, 0x70000
	global_load_dwordx4 v[140:143], v[50:51], off
	v_lshl_add_u64 v[50:51], v[0:1], 0, s[34:35]
	global_load_dwordx4 v[152:155], v[50:51], off
	v_lshl_add_u64 v[50:51], v[2:3], 0, s[34:35]
	global_load_dwordx4 v[172:175], v[50:51], off
	s_waitcnt vmcnt(31)
	ds_write_b128 v31, v[104:107]
	s_waitcnt vmcnt(30)
	ds_write_b128 v32, v[108:111]
	s_waitcnt vmcnt(29)
	ds_write_b128 v41, v[96:99]
	s_waitcnt vmcnt(28)
	ds_write_b128 v42, v[100:103]
	s_waitcnt lgkmcnt(5)
	v_mfma_f32_32x32x16_bf16 a[0:15], v[180:183], v[208:211], a[0:15]
	v_mfma_f32_32x32x16_bf16 a[16:31], v[180:183], v[212:215], a[16:31]
	v_mfma_f32_32x32x16_bf16 a[32:47], v[180:183], v[216:219], a[32:47]
	v_mfma_f32_32x32x16_bf16 a[48:63], v[180:183], v[220:223], a[48:63]
	ds_read_b128 v[180:183], v49 offset:9248
	ds_read_b128 v[184:187], v45 offset:64
	ds_read_b128 v[188:191], v45 offset:4672
	s_waitcnt lgkmcnt(7)
	v_mfma_f32_32x32x16_bf16 a[64:79], v[204:207], v[208:211], a[64:79]
	v_mfma_f32_32x32x16_bf16 a[80:95], v[204:207], v[212:215], a[80:95]
	v_mfma_f32_32x32x16_bf16 a[96:111], v[204:207], v[216:219], a[96:111]
	v_mfma_f32_32x32x16_bf16 a[112:127], v[204:207], v[220:223], a[112:127]
	ds_read_b128 v[204:207], v49 offset:13856
	ds_read_b128 v[192:195], v45 offset:9280
	ds_read_b128 v[196:199], v45 offset:13888
	s_waitcnt lgkmcnt(5)
	v_mfma_f32_32x32x16_bf16 a[128:143], v[180:183], v[208:211], a[128:143]
	v_mfma_f32_32x32x16_bf16 a[144:159], v[180:183], v[212:215], a[144:159]
	v_mfma_f32_32x32x16_bf16 a[160:175], v[180:183], v[216:219], a[160:175]
	v_mfma_f32_32x32x16_bf16 a[176:191], v[180:183], v[220:223], a[176:191]
	ds_read_b128 v[180:183], v49 offset:64
	s_waitcnt lgkmcnt(3)
	v_mfma_f32_32x32x16_bf16 a[192:207], v[204:207], v[208:211], a[192:207]
	v_mfma_f32_32x32x16_bf16 a[208:223], v[204:207], v[212:215], a[208:223]
	v_mfma_f32_32x32x16_bf16 a[224:239], v[204:207], v[216:219], a[224:239]
	v_mfma_f32_32x32x16_bf16 a[240:255], v[204:207], v[220:223], a[240:255]
	ds_read_b128 v[204:207], v49 offset:4672
	s_waitcnt vmcnt(27)
	ds_write_b128 v37, v[116:119]
	s_waitcnt vmcnt(26)
	ds_write_b128 v38, v[120:123]
	s_waitcnt vmcnt(25)
	ds_write_b128 v39, v[128:131]
	s_waitcnt vmcnt(24)
	ds_write_b128 v40, v[132:135]
	s_waitcnt lgkmcnt(5)
	v_mfma_f32_32x32x16_bf16 a[0:15], v[180:183], v[184:187], a[0:15]
	v_mfma_f32_32x32x16_bf16 a[16:31], v[180:183], v[188:191], a[16:31]
	v_mfma_f32_32x32x16_bf16 a[32:47], v[180:183], v[192:195], a[32:47]
	v_mfma_f32_32x32x16_bf16 a[48:63], v[180:183], v[196:199], a[48:63]
	ds_read_b128 v[180:183], v49 offset:9280
	ds_read_b128 v[208:211], v45 offset:96
	ds_read_b128 v[212:215], v45 offset:4704
	s_waitcnt lgkmcnt(7)
	v_mfma_f32_32x32x16_bf16 a[64:79], v[204:207], v[184:187], a[64:79]
	v_mfma_f32_32x32x16_bf16 a[80:95], v[204:207], v[188:191], a[80:95]
	v_mfma_f32_32x32x16_bf16 a[96:111], v[204:207], v[192:195], a[96:111]
	v_mfma_f32_32x32x16_bf16 a[112:127], v[204:207], v[196:199], a[112:127]
	ds_read_b128 v[204:207], v49 offset:13888
	ds_read_b128 v[216:219], v45 offset:9312
	ds_read_b128 v[220:223], v45 offset:13920
	s_waitcnt lgkmcnt(5)
	v_mfma_f32_32x32x16_bf16 a[128:143], v[180:183], v[184:187], a[128:143]
	v_mfma_f32_32x32x16_bf16 a[144:159], v[180:183], v[188:191], a[144:159]
	v_mfma_f32_32x32x16_bf16 a[160:175], v[180:183], v[192:195], a[160:175]
	v_mfma_f32_32x32x16_bf16 a[176:191], v[180:183], v[196:199], a[176:191]
	ds_read_b128 v[180:183], v49 offset:96
	s_waitcnt lgkmcnt(3)
	v_mfma_f32_32x32x16_bf16 a[192:207], v[204:207], v[184:187], a[192:207]
	v_mfma_f32_32x32x16_bf16 a[208:223], v[204:207], v[188:191], a[208:223]
	v_mfma_f32_32x32x16_bf16 a[224:239], v[204:207], v[192:195], a[224:239]
	v_mfma_f32_32x32x16_bf16 a[240:255], v[204:207], v[196:199], a[240:255]
	ds_read_b128 v[204:207], v49 offset:4704
	s_waitcnt vmcnt(23)
	ds_write_b128 v33, v[136:139]
	s_waitcnt vmcnt(22)
	ds_write_b128 v34, v[144:147]
	s_waitcnt vmcnt(21)
	ds_write_b128 v35, v[148:151]
	s_waitcnt vmcnt(20)
	ds_write_b128 v36, v[156:159]
	s_waitcnt lgkmcnt(5)
	v_mfma_f32_32x32x16_bf16 a[0:15], v[180:183], v[208:211], a[0:15]
	v_mfma_f32_32x32x16_bf16 a[16:31], v[180:183], v[212:215], a[16:31]
	v_mfma_f32_32x32x16_bf16 a[32:47], v[180:183], v[216:219], a[32:47]
	v_mfma_f32_32x32x16_bf16 a[48:63], v[180:183], v[220:223], a[48:63]
	ds_read_b128 v[180:183], v49 offset:9312
	s_waitcnt lgkmcnt(5)
	v_mfma_f32_32x32x16_bf16 a[64:79], v[204:207], v[208:211], a[64:79]
	v_mfma_f32_32x32x16_bf16 a[80:95], v[204:207], v[212:215], a[80:95]
	v_mfma_f32_32x32x16_bf16 a[96:111], v[204:207], v[216:219], a[96:111]
	v_mfma_f32_32x32x16_bf16 a[112:127], v[204:207], v[220:223], a[112:127]
	ds_read_b128 v[204:207], v49 offset:13920
	s_waitcnt lgkmcnt(1)
	v_mfma_f32_32x32x16_bf16 a[128:143], v[180:183], v[208:211], a[128:143]
	v_mfma_f32_32x32x16_bf16 a[144:159], v[180:183], v[212:215], a[144:159]
	v_mfma_f32_32x32x16_bf16 a[160:175], v[180:183], v[216:219], a[160:175]
	v_mfma_f32_32x32x16_bf16 a[176:191], v[180:183], v[220:223], a[176:191]
	s_waitcnt lgkmcnt(0)
	v_mfma_f32_32x32x16_bf16 a[192:207], v[204:207], v[208:211], a[192:207]
	v_mfma_f32_32x32x16_bf16 a[208:223], v[204:207], v[212:215], a[208:223]
	v_mfma_f32_32x32x16_bf16 a[224:239], v[204:207], v[216:219], a[224:239]
	v_mfma_f32_32x32x16_bf16 a[240:255], v[204:207], v[220:223], a[240:255]
	s_waitcnt vmcnt(19)
	ds_write_b128 v43, v[160:163]
	s_waitcnt vmcnt(18)
	ds_write_b128 v44, v[164:167]
	s_waitcnt vmcnt(17)
	ds_write_b128 v46, v[168:171]
	s_waitcnt vmcnt(16)
	ds_write_b128 v47, v[176:179]

; #define GLOAD(RA, RB, kt) { _Pragma("unroll") for (int i = 0; i < 8; ++i) { const int ia = (tail && i >= 4) ? i - 4 : i; \
;     RA[i] = *(const u32x4*)(abase + ((size_t)(32 * ia) * lda + (kt) * 64) * 2 + aoff); RB[i] = *(const u32x4*)(bbase + ((size_t)(32 * i) * K + (kt) * 64) * 2 + boff); } }
; template <int EPI>
; DEV void gemm_tile(CParams& p, int layer, const bf16_t* __restrict__ A, int lda, const bf16_t* __restrict__ Bt, int K, int m0, int n0, int nt, char* lds, const int swave) {
;     ...
;     const bool more = kt + 2 < nk;
;     if (kt + 3 < nk) GLOAD(ra1, rb1, kt + 3);
;     COMPUTE(1, ra0, rb0, 0, more);
;     __syncthreads();
.LBB0_939:
	v_add_u32_e32 v224, 0x1b000, v29
	v_add_u32_e32 v225, 0x12000, v45
	s_andn2_b64 vcc, exec, s[60:61]
	s_cbranch_vccnz .Lpg_i3_nomore
	ds_read_b128 v[184:187], v225
	ds_read_b128 v[188:191], v225 offset:4608
	ds_read_b128 v[192:195], v225 offset:9216
	ds_read_b128 v[196:199], v225 offset:13824
	ds_read_b128 v[180:183], v224
	ds_read_b128 v[204:207], v224 offset:4608
	s_waitcnt lgkmcnt(1)
	v_mfma_f32_32x32x16_bf16 a[0:15], v[180:183], v[184:187], a[0:15]
	v_mfma_f32_32x32x16_bf16 a[16:31], v[180:183], v[188:191], a[16:31]
	v_mfma_f32_32x32x16_bf16 a[32:47], v[180:183], v[192:195], a[32:47]
	v_mfma_f32_32x32x16_bf16 a[48:63], v[180:183], v[196:199], a[48:63]
	ds_read_b128 v[180:183], v224 offset:9216
	ds_read_b128 v[208:211], v225 offset:32
	ds_read_b128 v[212:215], v225 offset:4640
	s_lshl_b32 s34, s42, 7
	v_lshl_add_u64 v[50:51], v[0:1], 0, s[34:35]
	v_lshl_add_u64 v[96:97], v[2:3], 0, s[34:35]
	global_load_dwordx4 v[104:107], v[50:51], off offset:384
	global_load_dwordx4 v[108:111], v[96:97], off offset:384
	v_add_co_u32_e32 v50, vcc, 0x10000, v50
	v_lshl_add_u64 v[120:121], v[6:7], 0, s[34:35]
	v_addc_co_u32_e32 v51, vcc, 0, v51, vcc
	v_add_co_u32_e32 v100, vcc, 0x10000, v96
	v_lshl_add_u64 v[132:133], v[10:11], 0, s[34:35]
	v_addc_co_u32_e32 v101, vcc, 0, v97, vcc
	global_load_dwordx4 v[96:99], v[50:51], off offset:384
	s_nop 0
	global_load_dwordx4 v[100:103], v[100:101], off offset:384
	s_waitcnt lgkmcnt(3)
	v_mfma_f32_32x32x16_bf16 a[64:79], v[204:207], v[184:187], a[64:79]
	v_mfma_f32_32x32x16_bf16 a[80:95], v[204:207], v[188:191], a[80:95]
	v_mfma_f32_32x32x16_bf16 a[96:111], v[204:207], v[192:195], a[96:111]
	v_mfma_f32_32x32x16_bf16 a[112:127], v[204:207], v[196:199], a[112:127]
	ds_read_b128 v[204:207], v224 offset:13824
	ds_read_b128 v[216:219], v225 offset:9248
	ds_read_b128 v[220:223], v225 offset:13856
	v_lshl_add_u64 v[50:51], v[4:5], 0, s[34:35]
	global_load_dwordx4 v[116:119], v[50:51], off offset:384
	s_nop 0
	global_load_dwordx4 v[120:123], v[120:121], off offset:384
	v_lshl_add_u64 v[50:51], v[8:9], 0, s[34:35]
	global_load_dwordx4 v[128:131], v[50:51], off offset:384
	s_nop 0
	global_load_dwordx4 v[132:135], v[132:133], off offset:384
	s_waitcnt lgkmcnt(5)
	v_mfma_f32_32x32x16_bf16 a[128:143], v[180:183], v[184:187], a[128:143]
	v_mfma_f32_32x32x16_bf16 a[144:159], v[180:183], v[188:191], a[144:159]
	v_mfma_f32_32x32x16_bf16 a[160:175], v[180:183], v[192:195], a[160:175]
	v_mfma_f32_32x32x16_bf16 a[176:191], v[180:183], v[196:199], a[176:191]
	ds_read_b128 v[180:183], v224 offset:32
	v_lshl_add_u64 v[50:51], v[12:13], 0, s[34:35]
	v_lshl_add_u64 v[144:145], v[14:15], 0, s[34:35]
	global_load_dwordx4 v[136:139], v[50:51], off offset:384
	s_nop 0
	global_load_dwordx4 v[144:147], v[144:145], off offset:384
	v_lshl_add_u64 v[50:51], v[16:17], 0, s[34:35]
	v_lshl_add_u64 v[156:157], v[18:19], 0, s[34:35]
	global_load_dwordx4 v[148:151], v[50:51], off offset:384
	s_nop 0
	global_load_dwordx4 v[156:159], v[156:157], off offset:384
	s_waitcnt lgkmcnt(3)
	v_mfma_f32_32x32x16_bf16 a[192:207], v[204:207], v[184:187], a[192:207]
	v_mfma_f32_32x32x16_bf16 a[208:223], v[204:207], v[188:191], a[208:223]
	v_mfma_f32_32x32x16_bf16 a[224:239], v[204:207], v[192:195], a[224:239]
	v_mfma_f32_32x32x16_bf16 a[240:255], v[204:207], v[196:199], a[240:255]
	ds_read_b128 v[204:207], v224 offset:4640
	v_lshl_add_u64 v[50:51], v[20:21], 0, s[34:35]
	v_lshl_add_u64 v[164:165], v[22:23], 0, s[34:35]
	global_load_dwordx4 v[160:163], v[50:51], off offset:384
	s_nop 0
	global_load_dwordx4 v[164:167], v[164:165], off offset:384
	v_lshl_add_u64 v[50:51], v[24:25], 0, s[34:35]
	v_lshl_add_u64 v[176:177], v[26:27], 0, s[34:35]
	global_load_dwordx4 v[168:171], v[50:51], off offset:384
	s_nop 0
	global_load_dwordx4 v[176:179], v[176:177], off offset:384
	s_waitcnt vmcnt(31)
	ds_write_b128 v30, v[52:55]
	s_waitcnt vmcnt(30)
	ds_write_b128 v30, v[56:59] offset:36864
	s_waitcnt vmcnt(29)
	ds_write_b128 v30, v[60:63] offset:4608
	s_waitcnt vmcnt(28)
	ds_write_b128 v30, v[64:67] offset:41472
	s_waitcnt lgkmcnt(5)
	v_mfma_f32_32x32x16_bf16 a[0:15], v[180:183], v[208:211], a[0:15]
	v_mfma_f32_32x32x16_bf16 a[16:31], v[180:183], v[212:215], a[16:31]
	v_mfma_f32_32x32x16_bf16 a[32:47], v[180:183], v[216:219], a[32:47]
	v_mfma_f32_32x32x16_bf16 a[48:63], v[180:183], v[220:223], a[48:63]
	ds_read_b128 v[180:183], v224 offset:9248
	ds_read_b128 v[184:187], v225 offset:64
	ds_read_b128 v[188:191], v225 offset:4672
	s_waitcnt lgkmcnt(7)
; template <int EPI>
; DEV void gemm_tile(CParams& p, int layer, const bf16_t* __restrict__ A, int lda, const bf16_t* __restrict__ Bt, int K, int m0, int n0, int nt, char* lds, const int swave) {
;     ...
;     COMPUTE(1, ra0, rb0, 0, more);
;     __syncthreads();
	v_mfma_f32_32x32x16_bf16 a[64:79], v[204:207], v[208:211], a[64:79]
	v_mfma_f32_32x32x16_bf16 a[80:95], v[204:207], v[212:215], a[80:95]
	v_mfma_f32_32x32x16_bf16 a[96:111], v[204:207], v[216:219], a[96:111]
	v_mfma_f32_32x32x16_bf16 a[112:127], v[204:207], v[220:223], a[112:127]
	ds_read_b128 v[204:207], v224 offset:13856
	ds_read_b128 v[192:195], v225 offset:9280
	ds_read_b128 v[196:199], v225 offset:13888
	s_waitcnt lgkmcnt(5)
	v_mfma_f32_32x32x16_bf16 a[128:143], v[180:183], v[208:211], a[128:143]
	v_mfma_f32_32x32x16_bf16 a[144:159], v[180:183], v[212:215], a[144:159]
	v_mfma_f32_32x32x16_bf16 a[160:175], v[180:183], v[216:219], a[160:175]
	v_mfma_f32_32x32x16_bf16 a[176:191], v[180:183], v[220:223], a[176:191]
	ds_read_b128 v[180:183], v224 offset:64
	s_waitcnt lgkmcnt(3)
	v_mfma_f32_32x32x16_bf16 a[192:207], v[204:207], v[208:211], a[192:207]
	v_mfma_f32_32x32x16_bf16 a[208:223], v[204:207], v[212:215], a[208:223]
	v_mfma_f32_32x32x16_bf16 a[224:239], v[204:207], v[216:219], a[224:239]
	v_mfma_f32_32x32x16_bf16 a[240:255], v[204:207], v[220:223], a[240:255]
	ds_read_b128 v[204:207], v224 offset:4672
	s_waitcnt vmcnt(27)
	ds_write_b128 v30, v[68:71] offset:9216
	s_waitcnt vmcnt(26)
	ds_write_b128 v30, v[72:75] offset:46080
	s_waitcnt vmcnt(25)
	ds_write_b128 v30, v[76:79] offset:13824
	s_waitcnt vmcnt(24)
	ds_write_b128 v30, v[80:83] offset:50688
	s_waitcnt lgkmcnt(5)
	v_mfma_f32_32x32x16_bf16 a[0:15], v[180:183], v[184:187], a[0:15]
	v_mfma_f32_32x32x16_bf16 a[16:31], v[180:183], v[188:191], a[16:31]
	v_mfma_f32_32x32x16_bf16 a[32:47], v[180:183], v[192:195], a[32:47]
	v_mfma_f32_32x32x16_bf16 a[48:63], v[180:183], v[196:199], a[48:63]
	ds_read_b128 v[180:183], v224 offset:9280
	ds_read_b128 v[208:211], v225 offset:96
	ds_read_b128 v[212:215], v225 offset:4704
	s_waitcnt lgkmcnt(7)
	v_mfma_f32_32x32x16_bf16 a[64:79], v[204:207], v[184:187], a[64:79]
	v_mfma_f32_32x32x16_bf16 a[80:95], v[204:207], v[188:191], a[80:95]
	v_mfma_f32_32x32x16_bf16 a[96:111], v[204:207], v[192:195], a[96:111]
	v_mfma_f32_32x32x16_bf16 a[112:127], v[204:207], v[196:199], a[112:127]
	ds_read_b128 v[204:207], v224 offset:13888
	ds_read_b128 v[216:219], v225 offset:9312
	ds_read_b128 v[220:223], v225 offset:13920
	s_waitcnt lgkmcnt(5)
	v_mfma_f32_32x32x16_bf16 a[128:143], v[180:183], v[184:187], a[128:143]
	v_mfma_f32_32x32x16_bf16 a[144:159], v[180:183], v[188:191], a[144:159]
	v_mfma_f32_32x32x16_bf16 a[160:175], v[180:183], v[192:195], a[160:175]
	v_mfma_f32_32x32x16_bf16 a[176:191], v[180:183], v[196:199], a[176:191]
	ds_read_b128 v[180:183], v224 offset:96
	s_waitcnt lgkmcnt(3)
	v_mfma_f32_32x32x16_bf16 a[192:207], v[204:207], v[184:187], a[192:207]
	v_mfma_f32_32x32x16_bf16 a[208:223], v[204:207], v[188:191], a[208:223]
	v_mfma_f32_32x32x16_bf16 a[224:239], v[204:207], v[192:195], a[224:239]
	v_mfma_f32_32x32x16_bf16 a[240:255], v[204:207], v[196:199], a[240:255]
	ds_read_b128 v[204:207], v224 offset:4704
	s_waitcnt vmcnt(23)
	ds_write_b128 v30, v[84:87] offset:18432
	s_waitcnt vmcnt(22)
	ds_write_b128 v30, v[88:91] offset:55296
	s_waitcnt vmcnt(21)
	ds_write_b128 v30, v[92:95] offset:23040
	s_waitcnt vmcnt(20)
	ds_write_b128 v30, v[112:115] offset:59904
	s_waitcnt lgkmcnt(5)
	v_mfma_f32_32x32x16_bf16 a[0:15], v[180:183], v[208:211], a[0:15]
	v_mfma_f32_32x32x16_bf16 a[16:31], v[180:183], v[212:215], a[16:31]
	v_mfma_f32_32x32x16_bf16 a[32:47], v[180:183], v[216:219], a[32:47]
	v_mfma_f32_32x32x16_bf16 a[48:63], v[180:183], v[220:223], a[48:63]
	ds_read_b128 v[180:183], v224 offset:9312
	s_waitcnt lgkmcnt(5)
	v_mfma_f32_32x32x16_bf16 a[64:79], v[204:207], v[208:211], a[64:79]
	v_mfma_f32_32x32x16_bf16 a[80:95], v[204:207], v[212:215], a[80:95]
	v_mfma_f32_32x32x16_bf16 a[96:111], v[204:207], v[216:219], a[96:111]
	v_mfma_f32_32x32x16_bf16 a[112:127], v[204:207], v[220:223], a[112:127]
	ds_read_b128 v[204:207], v224 offset:13920
	s_waitcnt lgkmcnt(1)
	v_mfma_f32_32x32x16_bf16 a[128:143], v[180:183], v[208:211], a[128:143]
	v_mfma_f32_32x32x16_bf16 a[144:159], v[180:183], v[212:215], a[144:159]
	v_mfma_f32_32x32x16_bf16 a[160:175], v[180:183], v[216:219], a[160:175]
	v_mfma_f32_32x32x16_bf16 a[176:191], v[180:183], v[220:223], a[176:191]
	s_waitcnt lgkmcnt(0)
	v_mfma_f32_32x32x16_bf16 a[192:207], v[204:207], v[208:211], a[192:207]
	v_mfma_f32_32x32x16_bf16 a[208:223], v[204:207], v[212:215], a[208:223]
	v_mfma_f32_32x32x16_bf16 a[224:239], v[204:207], v[216:219], a[224:239]
	v_mfma_f32_32x32x16_bf16 a[240:255], v[204:207], v[220:223], a[240:255]
	s_waitcnt vmcnt(19)
	ds_write_b128 v30, v[124:127] offset:27648
	s_waitcnt vmcnt(18)
	ds_write_b128 v30, v[140:143] offset:64512
	s_waitcnt vmcnt(17)
	ds_write_b128 v30, v[152:155] offset:32256
	s_waitcnt vmcnt(16)
	ds_write_b128 v48, v[172:175]
	s_branch .LBB0_918
